# v9 minus the three per-unit s_waitcnt vmcnt(0) that hipcc left before the K-loop label of P5/P7/P9 (they drained the next tile's prefetch and the pre loads)
# baseline (speedup 1.0000x reference)
; #define PG8_STAGE(bufoff, gbase, voff) do { _Pragma("unroll") for (int _i = 0; _i < 2; ++_i) \
;         __builtin_amdgcn_global_load_lds((const unsigned*)((const char*)(gbase) + (voff)[_i]), (PG8_LAS unsigned*)(lds + (bufoff) + ldsw + _i * 8192), 16, 0, 0); } while (0)
; #define PG8_LDA(dst, b, h) do { if constexpr (FP8) { _Pragma("unroll") for (int m = 0; m < 4; ++m) dst##8[m] = PG8_LD8(lds + PG8_SA(b, h) + aoff + m * 2048); } \
;         else { _Pragma("unroll") for (int m = 0; m < 4; ++m) _Pragma("unroll") for (int k = 0; k < 2; ++k) dst[m][k] = *(const PG8_LAS bf16x8*)(lds + PG8_SA(b, h) + aoff + m * 2048 + k * 1024); } } while (0)
; #define PG8_WAIT_V(n) asm volatile("s_waitcnt vmcnt(" #n ")" ::: "memory")
; #define PG8_WAIT_L(n) asm volatile("s_waitcnt lgkmcnt(" #n ")" ::: "memory")
; #define PG8_BAR __builtin_amdgcn_s_barrier()
; template <class Epi, class Sched, bool ALIGN_EPI = false, bool SP2 = false, bool FP8 = false, bool I8 = false>
; __device__ __forceinline__ void gemm_phase(PG8_LAS unsigned char* lds, const Gemm g, const Sched& S, const Epi& E, const SplitK sk) {
;     ...
;         const bool has_next = S.next(ui + 1, nxt);
;         const char* nA = has_next ? (const char*)g.A + (size_t)nxt.pm * tstep + (size_t)nxt.kt0 * kstep : cA; const char* nB = has_next ? (const char*)g.Bt + (size_t)nxt.pn * tstep + (size_t)nxt.kt0 * kstep : cB;
;         const int nt = cur.nkt;
;         for (int t = 0; t < nt; t += 2) {
;             const bool last = (t == nt - 2);
;             const char* a1 = cA + (size_t)(t + 1) * kstep;
;             const char* a2 = last ? nA : cA + (size_t)(t + 2) * kstep; const char* b2 = last ? nB : cB + (size_t)(t + 2) * kstep;
;             const char* a3 = a2 + kstep; const char* b3 = b2 + kstep;
;             if (last && has_next) S.a_ready(nxt);
;             if constexpr (SP2) {
;             PG8_LDB(B0, 0, 0); PG8_LDB(B1, 0, 1); PG8_SCHED; PG8_LDA(At, 0, 0); PG8_STAGE(PG8_SA(1, 1), a1 + hstep, voffA);
;             PG8_WAIT_V(8); PG8_WAIT_L(0); PG8_BAR; PG8_MMA(0, 0, At, B0); PG8_MMA(0, 1, At, B1); PG8_BAR; PG8_SCHED;
;     ...
; #pragma unroll
;         for (int a = 0; a < 2; ++a)
; #pragma unroll
;             for (int b = 0; b < 2; ++b)
; #pragma unroll
;                 for (int m = 0; m < 4; ++m)
; #pragma unroll
;                     for (int n = 0; n < 2; ++n) acc[a][b][m][n] = (f32x4){0.f, 0.f, 0.f, 0.f};
.LBB0_765:
	s_ashr_i32 s95, s94, 31
	s_lshl_b64 s[20:21], s[94:95], 20
	s_add_u32 s22, s50, s20
	s_addc_u32 s23, s51, s21
	s_ashr_i32 s85, s84, 31
	s_lshl_b64 s[20:21], s[84:85], 7
	s_add_u32 s34, s22, s20
	s_addc_u32 s35, s23, s21
	s_and_b64 s[22:23], s[18:19], exec
	s_cselect_b32 s68, s35, s3
	s_cselect_b32 s69, s34, s2
	s_ashr_i32 s97, s96, 31
	s_lshl_b64 s[22:23], s[96:97], 20
	s_add_u32 s22, s26, s22
	s_addc_u32 s23, s27, s23
	s_add_u32 s22, s22, s20
	s_addc_u32 s23, s23, s21
	s_and_b64 s[20:21], s[18:19], exec
	s_cselect_b32 s73, s23, s5
	s_cselect_b32 s85, s22, s4
	s_add_i32 s95, s59, -2
	s_add_u32 s2, s2, 0x80080
	s_addc_u32 s3, s3, 0
	s_add_u32 s97, s4, 0x100
	v_mov_b32_e32 v0, 0
	s_addc_u32 vcc_lo, s5, 0
	s_mov_b32 s4, 0
	v_mov_b32_e32 v1, v0
	v_mov_b32_e32 v2, v0
	v_mov_b32_e32 v3, v0
	v_mov_b32_e32 v4, v0
	v_mov_b32_e32 v5, v0
	v_mov_b32_e32 v6, v0
	v_mov_b32_e32 v7, v0
	v_mov_b32_e32 v8, v0
	v_mov_b32_e32 v9, v0
	v_mov_b32_e32 v10, v0
	v_mov_b32_e32 v11, v0
	v_mov_b32_e32 v12, v0
	v_mov_b32_e32 v13, v0
	v_mov_b32_e32 v14, v0
	v_mov_b32_e32 v15, v0
	v_mov_b32_e32 v24, v0
	v_mov_b32_e32 v25, v0
	v_mov_b32_e32 v26, v0
	v_mov_b32_e32 v27, v0
	v_mov_b32_e32 v28, v0
	v_mov_b32_e32 v29, v0
	v_mov_b32_e32 v30, v0
	v_mov_b32_e32 v31, v0
	v_mov_b32_e32 v40, v0
	v_mov_b32_e32 v41, v0
	v_mov_b32_e32 v42, v0
	v_mov_b32_e32 v43, v0
	v_mov_b32_e32 v44, v0
	v_mov_b32_e32 v45, v0
	v_mov_b32_e32 v46, v0
	v_mov_b32_e32 v47, v0
	v_mov_b32_e32 v16, v0
	v_mov_b32_e32 v17, v0
	v_mov_b32_e32 v18, v0
	v_mov_b32_e32 v19, v0
	v_mov_b32_e32 v20, v0
	v_mov_b32_e32 v21, v0
	v_mov_b32_e32 v22, v0
	v_mov_b32_e32 v23, v0
	v_mov_b32_e32 v32, v0
	v_mov_b32_e32 v33, v0
	v_mov_b32_e32 v34, v0
	v_mov_b32_e32 v35, v0
	v_mov_b32_e32 v36, v0
	v_mov_b32_e32 v37, v0
	v_mov_b32_e32 v38, v0
	v_mov_b32_e32 v39, v0
	v_mov_b32_e32 v48, v0
	v_mov_b32_e32 v49, v0
	v_mov_b32_e32 v50, v0
	v_mov_b32_e32 v51, v0
	v_mov_b32_e32 v52, v0
	v_mov_b32_e32 v53, v0
	v_mov_b32_e32 v54, v0
	v_mov_b32_e32 v55, v0
	v_mov_b32_e32 v56, v0
	v_mov_b32_e32 v57, v0
	v_mov_b32_e32 v58, v0
	v_mov_b32_e32 v59, v0
	v_mov_b32_e32 v60, v0
	v_mov_b32_e32 v61, v0
	v_mov_b32_e32 v62, v0
	v_mov_b32_e32 v63, v0
	v_mov_b32_e32 v64, v0
	v_mov_b32_e32 v65, v0
	v_mov_b32_e32 v66, v0
	v_mov_b32_e32 v67, v0
	v_mov_b32_e32 v68, v0
	v_mov_b32_e32 v69, v0
	v_mov_b32_e32 v70, v0
	v_mov_b32_e32 v71, v0
	v_mov_b32_e32 v72, v0
	v_mov_b32_e32 v73, v0
	v_mov_b32_e32 v74, v0
	v_mov_b32_e32 v75, v0
	v_mov_b32_e32 v76, v0
	v_mov_b32_e32 v77, v0
	v_mov_b32_e32 v78, v0
	v_mov_b32_e32 v79, v0
	v_mov_b32_e32 v88, v0
	v_mov_b32_e32 v89, v0
	v_mov_b32_e32 v90, v0
	v_mov_b32_e32 v91, v0
	v_mov_b32_e32 v92, v0
	v_mov_b32_e32 v93, v0
	v_mov_b32_e32 v94, v0
	v_mov_b32_e32 v95, v0
	v_mov_b32_e32 v104, v0
	v_mov_b32_e32 v105, v0
	v_mov_b32_e32 v106, v0
	v_mov_b32_e32 v107, v0
	v_mov_b32_e32 v108, v0
	v_mov_b32_e32 v109, v0
	v_mov_b32_e32 v110, v0
	v_mov_b32_e32 v111, v0
	v_mov_b32_e32 v80, v0
	v_mov_b32_e32 v81, v0
	v_mov_b32_e32 v82, v0
	v_mov_b32_e32 v83, v0
	v_mov_b32_e32 v84, v0
	v_mov_b32_e32 v85, v0
	v_mov_b32_e32 v86, v0
	v_mov_b32_e32 v87, v0
	v_mov_b32_e32 v96, v0
	v_mov_b32_e32 v97, v0
	v_mov_b32_e32 v98, v0
	v_mov_b32_e32 v99, v0
	v_mov_b32_e32 v100, v0
	v_mov_b32_e32 v101, v0
	v_mov_b32_e32 v102, v0
	v_mov_b32_e32 v103, v0
	v_mov_b32_e32 v112, v0
	v_mov_b32_e32 v113, v0
	v_mov_b32_e32 v114, v0
	v_mov_b32_e32 v115, v0
	v_mov_b32_e32 v116, v0
	v_mov_b32_e32 v117, v0
	v_mov_b32_e32 v118, v0
	v_mov_b32_e32 v119, v0
	v_mov_b32_e32 v120, v0
	v_mov_b32_e32 v121, v0
	v_mov_b32_e32 v122, v0
	v_mov_b32_e32 v123, v0
	v_mov_b32_e32 v124, v0
	v_mov_b32_e32 v125, v0
	v_mov_b32_e32 v126, v0
	v_mov_b32_e32 v127, v0
.LBB0_766:
	ds_read_b128 v[128:131], v163
	ds_read_b128 v[132:135], v163 offset:1024
	ds_read_b128 v[152:155], v163 offset:2048
	ds_read_b128 v[156:159], v163 offset:3072
	ds_read_b128 v[166:169], v164
	ds_read_b128 v[170:173], v164 offset:1024
	ds_read_b128 v[174:177], v164 offset:2048
	ds_read_b128 v[178:181], v164 offset:3072
	s_add_i32 vcc_hi, s4, 2
	s_add_u32 s5, s2, 0xfff80080
	s_addc_u32 s20, s3, -1
	s_cmp_eq_u32 s95, s4
	s_cselect_b32 s4, s85, s97
	s_cselect_b32 s21, s68, s20
	s_cselect_b32 s20, s69, s5
	s_cselect_b32 s5, s73, vcc_lo
	v_lshl_add_u64 v[160:161], s[2:3], 0, v[146:147]
	s_add_i32 m0, s29, 0xc000
	ds_read_b128 v[182:185], v165
	ds_read_b128 v[186:189], v165 offset:1024
	ds_read_b128 v[190:193], v165 offset:2048
	ds_read_b128 v[194:197], v165 offset:3072
	ds_read_b128 v[198:201], v165 offset:4096
	ds_read_b128 v[202:205], v165 offset:5120
	ds_read_b128 v[206:209], v165 offset:6144
	ds_read_b128 v[212:215], v165 offset:7168
	global_load_lds_dwordx4 v[160:161], off
	v_lshl_add_u64 v[160:161], s[2:3], 0, v[148:149]
	s_add_i32 m0, s29, 0xe000
	s_nop 0
	global_load_lds_dwordx4 v[160:161], off
	s_waitcnt vmcnt(8)
	s_waitcnt lgkmcnt(0)
	s_barrier
; #define PG8_STAGE(bufoff, gbase, voff) do { _Pragma("unroll") for (int _i = 0; _i < 2; ++_i) \
;         __builtin_amdgcn_global_load_lds((const unsigned*)((const char*)(gbase) + (voff)[_i]), (PG8_LAS unsigned*)(lds + (bufoff) + ldsw + _i * 8192), 16, 0, 0); } while (0)
; #define PG8_LDA(dst, b, h) do { if constexpr (FP8) { _Pragma("unroll") for (int m = 0; m < 4; ++m) dst##8[m] = PG8_LD8(lds + PG8_SA(b, h) + aoff + m * 2048); } \
;         else { _Pragma("unroll") for (int m = 0; m < 4; ++m) _Pragma("unroll") for (int k = 0; k < 2; ++k) dst[m][k] = *(const PG8_LAS bf16x8*)(lds + PG8_SA(b, h) + aoff + m * 2048 + k * 1024); } } while (0)
; #define PG8_WAIT_V(n) asm volatile("s_waitcnt vmcnt(" #n ")" ::: "memory")
; #define PG8_WAIT_L(n) asm volatile("s_waitcnt lgkmcnt(" #n ")" ::: "memory")
; #define PG8_BAR __builtin_amdgcn_s_barrier()
; #define PG8_SCHED __builtin_amdgcn_sched_barrier(0)
; template <class Epi, class Sched, bool ALIGN_EPI = false, bool SP2 = false, bool FP8 = false, bool I8 = false>
; __device__ __forceinline__ void gemm_phase(PG8_LAS unsigned char* lds, const Gemm g, const Sched& S, const Epi& E, const SplitK sk) {
;     ...
;             PG8_WAIT_V(8); PG8_WAIT_L(0); PG8_BAR; PG8_MMA(0, 0, At, B0); PG8_MMA(0, 1, At, B1); PG8_BAR; PG8_SCHED;
;             PG8_LDA(At, 0, 1); PG8_STAGE(PG8_SB(0, 0), b2, voffB); PG8_STAGE(PG8_SB(0, 1), b2 + hstep, voffB); PG8_STAGE(PG8_SA(0, 0), a2, voffA);
;             PG8_WAIT_V(8); PG8_WAIT_L(0); PG8_BAR; PG8_MMA(1, 0, At, B0); PG8_MMA(1, 1, At, B1); PG8_BAR; PG8_SCHED;
	s_setprio 1
	s_waitcnt lgkmcnt(0)
	v_mfma_f32_16x16x32_bf16 v[124:127], v[128:131], v[182:185], v[124:127]
	v_mfma_f32_16x16x32_bf16 v[120:123], v[152:155], v[182:185], v[120:123]
	v_mfma_f32_16x16x32_bf16 v[116:119], v[128:131], v[190:193], v[116:119]
	v_mfma_f32_16x16x32_bf16 v[112:115], v[152:155], v[190:193], v[112:115]
	v_mfma_f32_16x16x32_bf16 v[100:103], v[128:131], v[198:201], v[100:103]
	v_mfma_f32_16x16x32_bf16 v[96:99], v[152:155], v[198:201], v[96:99]
	v_mfma_f32_16x16x32_bf16 v[84:87], v[128:131], v[206:209], v[84:87]
	v_mfma_f32_16x16x32_bf16 v[80:83], v[152:155], v[206:209], v[80:83]
	v_mfma_f32_16x16x32_bf16 v[124:127], v[132:135], v[186:189], v[124:127]
	v_mfma_f32_16x16x32_bf16 v[120:123], v[156:159], v[186:189], v[120:123]
	v_mfma_f32_16x16x32_bf16 v[116:119], v[132:135], v[194:197], v[116:119]
	v_mfma_f32_16x16x32_bf16 v[112:115], v[156:159], v[194:197], v[112:115]
	v_mfma_f32_16x16x32_bf16 v[100:103], v[132:135], v[202:205], v[100:103]
	v_mfma_f32_16x16x32_bf16 v[96:99], v[156:159], v[202:205], v[96:99]
	v_mfma_f32_16x16x32_bf16 v[84:87], v[132:135], v[212:215], v[84:87]
	v_mfma_f32_16x16x32_bf16 v[80:83], v[156:159], v[212:215], v[80:83]
	s_setprio 0
	s_setprio 1
	v_mfma_f32_16x16x32_bf16 v[108:111], v[166:169], v[182:185], v[108:111]
	v_mfma_f32_16x16x32_bf16 v[104:107], v[174:177], v[182:185], v[104:107]
	v_mfma_f32_16x16x32_bf16 v[92:95], v[166:169], v[190:193], v[92:95]
	v_mfma_f32_16x16x32_bf16 v[88:91], v[174:177], v[190:193], v[88:91]
	v_mfma_f32_16x16x32_bf16 v[76:79], v[166:169], v[198:201], v[76:79]
	v_mfma_f32_16x16x32_bf16 v[72:75], v[174:177], v[198:201], v[72:75]
	v_mfma_f32_16x16x32_bf16 v[68:71], v[166:169], v[206:209], v[68:71]
	v_mfma_f32_16x16x32_bf16 v[64:67], v[174:177], v[206:209], v[64:67]
	v_mfma_f32_16x16x32_bf16 v[108:111], v[170:173], v[186:189], v[108:111]
	v_mfma_f32_16x16x32_bf16 v[104:107], v[178:181], v[186:189], v[104:107]
	v_mfma_f32_16x16x32_bf16 v[92:95], v[170:173], v[194:197], v[92:95]
	v_mfma_f32_16x16x32_bf16 v[88:91], v[178:181], v[194:197], v[88:91]
	v_mfma_f32_16x16x32_bf16 v[76:79], v[170:173], v[202:205], v[76:79]
	v_mfma_f32_16x16x32_bf16 v[72:75], v[178:181], v[202:205], v[72:75]
	v_mfma_f32_16x16x32_bf16 v[68:71], v[170:173], v[212:215], v[68:71]
	v_mfma_f32_16x16x32_bf16 v[64:67], v[178:181], v[212:215], v[64:67]
	s_setprio 0
	s_barrier
	s_add_i32 s82, s56, s28
	v_lshl_add_u64 v[160:161], s[4:5], 0, v[138:139]
	s_mov_b32 m0, s82
	ds_read_b128 v[182:185], v165 offset:16384
	ds_read_b128 v[186:189], v165 offset:17408
	ds_read_b128 v[190:193], v165 offset:18432
	ds_read_b128 v[194:197], v165 offset:19456
	ds_read_b128 v[198:201], v165 offset:20480
	ds_read_b128 v[202:205], v165 offset:21504
	ds_read_b128 v[206:209], v165 offset:22528
	ds_read_b128 v[212:215], v165 offset:23552
	global_load_lds_dwordx4 v[160:161], off
	s_add_i32 m0, s82, 0x2000
	s_add_u32 s82, s4, 0x80000
	v_lshl_add_u64 v[216:217], s[4:5], 0, v[142:143]
	s_addc_u32 s83, s5, 0
	s_add_i32 s0, s57, s28
	global_load_lds_dwordx4 v[216:217], off
	v_lshl_add_u64 v[218:219], s[82:83], 0, v[138:139]
	s_mov_b32 m0, s0
	v_lshl_add_u64 v[220:221], s[20:21], 0, v[140:141]
	global_load_lds_dwordx4 v[218:219], off
	v_lshl_add_u64 v[218:219], s[82:83], 0, v[142:143]
	s_add_i32 m0, s0, 0x2000
	s_nop 0
	global_load_lds_dwordx4 v[218:219], off
	v_lshl_add_u64 v[218:219], s[20:21], 0, v[136:137]
	s_mov_b32 m0, s29
	s_nop 0
	global_load_lds_dwordx4 v[218:219], off
	s_mov_b32 m0, s30
	s_nop 0
	global_load_lds_dwordx4 v[220:221], off
	s_waitcnt vmcnt(8)
	s_waitcnt lgkmcnt(0)
	s_barrier
	s_setprio 1
	s_waitcnt lgkmcnt(0)
	v_mfma_f32_16x16x32_bf16 v[60:63], v[128:131], v[182:185], v[60:63]
	v_mfma_f32_16x16x32_bf16 v[56:59], v[152:155], v[182:185], v[56:59]
	v_mfma_f32_16x16x32_bf16 v[52:55], v[128:131], v[190:193], v[52:55]
	v_mfma_f32_16x16x32_bf16 v[48:51], v[152:155], v[190:193], v[48:51]
	v_mfma_f32_16x16x32_bf16 v[36:39], v[128:131], v[198:201], v[36:39]
	v_mfma_f32_16x16x32_bf16 v[32:35], v[152:155], v[198:201], v[32:35]
	v_mfma_f32_16x16x32_bf16 v[20:23], v[128:131], v[206:209], v[20:23]
	v_mfma_f32_16x16x32_bf16 v[16:19], v[152:155], v[206:209], v[16:19]
	v_mfma_f32_16x16x32_bf16 v[60:63], v[132:135], v[186:189], v[60:63]
	v_mfma_f32_16x16x32_bf16 v[56:59], v[156:159], v[186:189], v[56:59]
	v_mfma_f32_16x16x32_bf16 v[52:55], v[132:135], v[194:197], v[52:55]
	v_mfma_f32_16x16x32_bf16 v[48:51], v[156:159], v[194:197], v[48:51]
	v_mfma_f32_16x16x32_bf16 v[36:39], v[132:135], v[202:205], v[36:39]
	v_mfma_f32_16x16x32_bf16 v[32:35], v[156:159], v[202:205], v[32:35]
	v_mfma_f32_16x16x32_bf16 v[20:23], v[132:135], v[212:215], v[20:23]
	v_mfma_f32_16x16x32_bf16 v[16:19], v[156:159], v[212:215], v[16:19]
	s_setprio 0
	s_setprio 1
	v_mfma_f32_16x16x32_bf16 v[44:47], v[166:169], v[182:185], v[44:47]
	v_mfma_f32_16x16x32_bf16 v[40:43], v[174:177], v[182:185], v[40:43]
	v_mfma_f32_16x16x32_bf16 v[28:31], v[166:169], v[190:193], v[28:31]
	v_mfma_f32_16x16x32_bf16 v[24:27], v[174:177], v[190:193], v[24:27]
	v_mfma_f32_16x16x32_bf16 v[12:15], v[166:169], v[198:201], v[12:15]
	v_mfma_f32_16x16x32_bf16 v[8:11], v[174:177], v[198:201], v[8:11]
	v_mfma_f32_16x16x32_bf16 v[4:7], v[166:169], v[206:209], v[4:7]
	v_mfma_f32_16x16x32_bf16 v[0:3], v[174:177], v[206:209], v[0:3]
	v_mfma_f32_16x16x32_bf16 v[44:47], v[170:173], v[186:189], v[44:47]
	v_mfma_f32_16x16x32_bf16 v[40:43], v[178:181], v[186:189], v[40:43]
	v_mfma_f32_16x16x32_bf16 v[28:31], v[170:173], v[194:197], v[28:31]
	v_mfma_f32_16x16x32_bf16 v[24:27], v[178:181], v[194:197], v[24:27]
	v_mfma_f32_16x16x32_bf16 v[12:15], v[170:173], v[202:205], v[12:15]
	v_mfma_f32_16x16x32_bf16 v[8:11], v[178:181], v[202:205], v[8:11]
	v_mfma_f32_16x16x32_bf16 v[4:7], v[170:173], v[212:215], v[4:7]
	v_mfma_f32_16x16x32_bf16 v[0:3], v[178:181], v[212:215], v[0:3]
	s_setprio 0
	s_barrier
; #define PG8_STAGE(bufoff, gbase, voff) do { _Pragma("unroll") for (int _i = 0; _i < 2; ++_i) \
;         __builtin_amdgcn_global_load_lds((const unsigned*)((const char*)(gbase) + (voff)[_i]), (PG8_LAS unsigned*)(lds + (bufoff) + ldsw + _i * 8192), 16, 0, 0); } while (0)
; #define PG8_LDA(dst, b, h) do { if constexpr (FP8) { _Pragma("unroll") for (int m = 0; m < 4; ++m) dst##8[m] = PG8_LD8(lds + PG8_SA(b, h) + aoff + m * 2048); } \
;         else { _Pragma("unroll") for (int m = 0; m < 4; ++m) _Pragma("unroll") for (int k = 0; k < 2; ++k) dst[m][k] = *(const PG8_LAS bf16x8*)(lds + PG8_SA(b, h) + aoff + m * 2048 + k * 1024); } } while (0)
; #define PG8_LDB(dst, b, h) do { if constexpr (FP8) { _Pragma("unroll") for (int n = 0; n < 2; ++n) dst##8[n] = PG8_LD8(lds + PG8_SB(b, h) + boff + n * 2048); } \
;         else { _Pragma("unroll") for (int n = 0; n < 2; ++n) _Pragma("unroll") for (int k = 0; k < 2; ++k) dst[n][k] = *(const PG8_LAS bf16x8*)(lds + PG8_SB(b, h) + boff + n * 2048 + k * 1024); } } while (0)
; #define PG8_WAIT_V(n) asm volatile("s_waitcnt vmcnt(" #n ")" ::: "memory")
; #define PG8_WAIT_L(n) asm volatile("s_waitcnt lgkmcnt(" #n ")" ::: "memory")
; #define PG8_BAR __builtin_amdgcn_s_barrier()
; #define PG8_SCHED __builtin_amdgcn_sched_barrier(0)
; template <class Epi, class Sched, bool ALIGN_EPI = false, bool SP2 = false, bool FP8 = false, bool I8 = false>
; __device__ __forceinline__ void gemm_phase(PG8_LAS unsigned char* lds, const Gemm g, const Sched& S, const Epi& E, const SplitK sk) {
;     ...
;             PG8_LDB(B0, 1, 0); PG8_LDB(B1, 1, 1); PG8_SCHED; PG8_LDA(At, 1, 0); PG8_STAGE(PG8_SA(0, 1), a2 + hstep, voffA);
;             PG8_WAIT_V(8); PG8_WAIT_L(0); PG8_BAR; PG8_MMA(0, 0, At, B0); PG8_MMA(0, 1, At, B1); PG8_BAR; PG8_SCHED;
	s_add_i32 s0, 0, 0x18000
	v_add_u32_e32 v144, s0, v162
	s_add_i32 s1, 0, 0x1c000
	ds_read_b128 v[128:131], v144
	ds_read_b128 v[132:135], v144 offset:1024
	ds_read_b128 v[152:155], v144 offset:2048
	ds_read_b128 v[156:159], v144 offset:3072
	v_add_u32_e32 v144, s1, v162
	ds_read_b128 v[166:169], v144
	ds_read_b128 v[170:173], v144 offset:1024
	ds_read_b128 v[174:177], v144 offset:2048
	ds_read_b128 v[178:181], v144 offset:3072
	s_add_u32 s20, s20, 0x80000
	s_addc_u32 s21, s21, 0
	s_mov_b32 m0, s31
	v_lshl_add_u64 v[222:223], s[20:21], 0, v[136:137]
	ds_read_b128 v[182:185], v165 offset:32768
	ds_read_b128 v[186:189], v165 offset:33792
	ds_read_b128 v[190:193], v165 offset:34816
	ds_read_b128 v[194:197], v165 offset:35840
	ds_read_b128 v[198:201], v165 offset:36864
	ds_read_b128 v[202:205], v165 offset:37888
	ds_read_b128 v[206:209], v165 offset:38912
	ds_read_b128 v[212:215], v165 offset:39936
	global_load_lds_dwordx4 v[222:223], off
	v_lshl_add_u64 v[222:223], s[20:21], 0, v[140:141]
	s_mov_b32 m0, s33
	s_nop 0
	global_load_lds_dwordx4 v[222:223], off
	s_waitcnt vmcnt(8)
	s_waitcnt lgkmcnt(0)
	s_barrier
	s_setprio 1
	s_waitcnt lgkmcnt(0)
	v_mfma_f32_16x16x32_bf16 v[124:127], v[128:131], v[182:185], v[124:127]
	v_mfma_f32_16x16x32_bf16 v[120:123], v[152:155], v[182:185], v[120:123]
	v_mfma_f32_16x16x32_bf16 v[116:119], v[128:131], v[190:193], v[116:119]
	v_mfma_f32_16x16x32_bf16 v[112:115], v[152:155], v[190:193], v[112:115]
	v_mfma_f32_16x16x32_bf16 v[100:103], v[128:131], v[198:201], v[100:103]
	v_mfma_f32_16x16x32_bf16 v[96:99], v[152:155], v[198:201], v[96:99]
	v_mfma_f32_16x16x32_bf16 v[84:87], v[128:131], v[206:209], v[84:87]
	v_mfma_f32_16x16x32_bf16 v[80:83], v[152:155], v[206:209], v[80:83]
	v_mfma_f32_16x16x32_bf16 v[124:127], v[132:135], v[186:189], v[124:127]
	v_mfma_f32_16x16x32_bf16 v[120:123], v[156:159], v[186:189], v[120:123]
	v_mfma_f32_16x16x32_bf16 v[116:119], v[132:135], v[194:197], v[116:119]
	v_mfma_f32_16x16x32_bf16 v[112:115], v[156:159], v[194:197], v[112:115]
	v_mfma_f32_16x16x32_bf16 v[100:103], v[132:135], v[202:205], v[100:103]
	v_mfma_f32_16x16x32_bf16 v[96:99], v[156:159], v[202:205], v[96:99]
	v_mfma_f32_16x16x32_bf16 v[84:87], v[132:135], v[212:215], v[84:87]
	v_mfma_f32_16x16x32_bf16 v[80:83], v[156:159], v[212:215], v[80:83]
	s_setprio 0
	s_setprio 1
	v_mfma_f32_16x16x32_bf16 v[108:111], v[166:169], v[182:185], v[108:111]
	v_mfma_f32_16x16x32_bf16 v[104:107], v[174:177], v[182:185], v[104:107]
	v_mfma_f32_16x16x32_bf16 v[92:95], v[166:169], v[190:193], v[92:95]
	v_mfma_f32_16x16x32_bf16 v[88:91], v[174:177], v[190:193], v[88:91]
	v_mfma_f32_16x16x32_bf16 v[76:79], v[166:169], v[198:201], v[76:79]
	v_mfma_f32_16x16x32_bf16 v[72:75], v[174:177], v[198:201], v[72:75]
	v_mfma_f32_16x16x32_bf16 v[68:71], v[166:169], v[206:209], v[68:71]
	v_mfma_f32_16x16x32_bf16 v[64:67], v[174:177], v[206:209], v[64:67]
	v_mfma_f32_16x16x32_bf16 v[108:111], v[170:173], v[186:189], v[108:111]
	v_mfma_f32_16x16x32_bf16 v[104:107], v[178:181], v[186:189], v[104:107]
	v_mfma_f32_16x16x32_bf16 v[92:95], v[170:173], v[194:197], v[92:95]
	v_mfma_f32_16x16x32_bf16 v[88:91], v[178:181], v[194:197], v[88:91]
	v_mfma_f32_16x16x32_bf16 v[76:79], v[170:173], v[202:205], v[76:79]
	v_mfma_f32_16x16x32_bf16 v[72:75], v[178:181], v[202:205], v[72:75]
	v_mfma_f32_16x16x32_bf16 v[68:71], v[170:173], v[212:215], v[68:71]
	v_mfma_f32_16x16x32_bf16 v[64:67], v[178:181], v[212:215], v[64:67]
	s_setprio 0
	s_barrier
; #define PG8_STAGE(bufoff, gbase, voff) do { _Pragma("unroll") for (int _i = 0; _i < 2; ++_i) \
;         __builtin_amdgcn_global_load_lds((const unsigned*)((const char*)(gbase) + (voff)[_i]), (PG8_LAS unsigned*)(lds + (bufoff) + ldsw + _i * 8192), 16, 0, 0); } while (0)
; #define PG8_LDA(dst, b, h) do { if constexpr (FP8) { _Pragma("unroll") for (int m = 0; m < 4; ++m) dst##8[m] = PG8_LD8(lds + PG8_SA(b, h) + aoff + m * 2048); } \
;         else { _Pragma("unroll") for (int m = 0; m < 4; ++m) _Pragma("unroll") for (int k = 0; k < 2; ++k) dst[m][k] = *(const PG8_LAS bf16x8*)(lds + PG8_SA(b, h) + aoff + m * 2048 + k * 1024); } } while (0)
; #define PG8_WAIT_V(n) asm volatile("s_waitcnt vmcnt(" #n ")" ::: "memory")
; #define PG8_WAIT_L(n) asm volatile("s_waitcnt lgkmcnt(" #n ")" ::: "memory")
; #define PG8_BAR __builtin_amdgcn_s_barrier()
; #define PG8_SCHED __builtin_amdgcn_sched_barrier(0)
; template <class Epi, class Sched, bool ALIGN_EPI = false, bool SP2 = false, bool FP8 = false, bool I8 = false>
; __device__ __forceinline__ void gemm_phase(PG8_LAS unsigned char* lds, const Gemm g, const Sched& S, const Epi& E, const SplitK sk) {
;     ...
;             PG8_LDA(At, 1, 1); PG8_STAGE(PG8_SB(1, 0), b3, voffB); PG8_STAGE(PG8_SB(1, 1), b3 + hstep, voffB); PG8_STAGE(PG8_SA(1, 0), a3, voffA);
;             PG8_WAIT_V(8); PG8_WAIT_L(0); PG8_BAR; PG8_MMA(1, 0, At, B0); PG8_MMA(1, 1, At, B1); PG8_BAR; PG8_SCHED;
;     ...
;         if constexpr (ALIGN_EPI) { if (wr == 0) PG8_BAR; }
	s_add_i32 s0, s0, s28
	v_lshl_add_u64 v[160:161], v[160:161], 0, s[12:13]
	s_mov_b32 m0, s0
	ds_read_b128 v[182:185], v165 offset:49152
	ds_read_b128 v[186:189], v165 offset:50176
	ds_read_b128 v[190:193], v165 offset:51200
	ds_read_b128 v[194:197], v165 offset:52224
	ds_read_b128 v[198:201], v165 offset:53248
	ds_read_b128 v[202:205], v165 offset:54272
	ds_read_b128 v[206:209], v165 offset:55296
	ds_read_b128 v[212:215], v165 offset:56320
	global_load_lds_dwordx4 v[160:161], off
	s_add_i32 m0, s0, 0x2000
	s_add_u32 s4, s4, 0x80080
	v_lshl_add_u64 v[160:161], v[216:217], 0, s[12:13]
	s_addc_u32 s5, s5, 0
	s_add_i32 s0, s1, s28
	global_load_lds_dwordx4 v[160:161], off
	v_lshl_add_u64 v[160:161], s[4:5], 0, v[138:139]
	s_mov_b32 m0, s0
	s_nop 0
	global_load_lds_dwordx4 v[160:161], off
	v_lshl_add_u64 v[160:161], s[4:5], 0, v[142:143]
	s_add_i32 m0, s0, 0x2000
	s_nop 0
	global_load_lds_dwordx4 v[160:161], off
	v_lshl_add_u64 v[160:161], v[218:219], 0, s[12:13]
	s_mov_b32 m0, s54
	s_nop 0
	global_load_lds_dwordx4 v[160:161], off
	v_lshl_add_u64 v[160:161], v[220:221], 0, s[12:13]
	s_mov_b32 m0, s55
	s_nop 0
	global_load_lds_dwordx4 v[160:161], off
	s_waitcnt vmcnt(8)
	s_waitcnt lgkmcnt(0)
	s_barrier
	s_setprio 1
	s_waitcnt lgkmcnt(0)
	v_mfma_f32_16x16x32_bf16 v[60:63], v[128:131], v[182:185], v[60:63]
	v_mfma_f32_16x16x32_bf16 v[56:59], v[152:155], v[182:185], v[56:59]
	v_mfma_f32_16x16x32_bf16 v[52:55], v[128:131], v[190:193], v[52:55]
	v_mfma_f32_16x16x32_bf16 v[48:51], v[152:155], v[190:193], v[48:51]
	v_mfma_f32_16x16x32_bf16 v[36:39], v[128:131], v[198:201], v[36:39]
	v_mfma_f32_16x16x32_bf16 v[32:35], v[152:155], v[198:201], v[32:35]
	v_mfma_f32_16x16x32_bf16 v[20:23], v[128:131], v[206:209], v[20:23]
	v_mfma_f32_16x16x32_bf16 v[16:19], v[152:155], v[206:209], v[16:19]
	v_mfma_f32_16x16x32_bf16 v[60:63], v[132:135], v[186:189], v[60:63]
	v_mfma_f32_16x16x32_bf16 v[56:59], v[156:159], v[186:189], v[56:59]
	v_mfma_f32_16x16x32_bf16 v[52:55], v[132:135], v[194:197], v[52:55]
	v_mfma_f32_16x16x32_bf16 v[48:51], v[156:159], v[194:197], v[48:51]
	v_mfma_f32_16x16x32_bf16 v[36:39], v[132:135], v[202:205], v[36:39]
	v_mfma_f32_16x16x32_bf16 v[32:35], v[156:159], v[202:205], v[32:35]
	v_mfma_f32_16x16x32_bf16 v[20:23], v[132:135], v[212:215], v[20:23]
	v_mfma_f32_16x16x32_bf16 v[16:19], v[156:159], v[212:215], v[16:19]
	s_setprio 0
	s_setprio 1
	v_mfma_f32_16x16x32_bf16 v[44:47], v[166:169], v[182:185], v[44:47]
	v_mfma_f32_16x16x32_bf16 v[40:43], v[174:177], v[182:185], v[40:43]
	v_mfma_f32_16x16x32_bf16 v[28:31], v[166:169], v[190:193], v[28:31]
	v_mfma_f32_16x16x32_bf16 v[24:27], v[174:177], v[190:193], v[24:27]
	v_mfma_f32_16x16x32_bf16 v[12:15], v[166:169], v[198:201], v[12:15]
	v_mfma_f32_16x16x32_bf16 v[8:11], v[174:177], v[198:201], v[8:11]
	v_mfma_f32_16x16x32_bf16 v[4:7], v[166:169], v[206:209], v[4:7]
	v_mfma_f32_16x16x32_bf16 v[0:3], v[174:177], v[206:209], v[0:3]
	v_mfma_f32_16x16x32_bf16 v[44:47], v[170:173], v[186:189], v[44:47]
	v_mfma_f32_16x16x32_bf16 v[40:43], v[178:181], v[186:189], v[40:43]
	v_mfma_f32_16x16x32_bf16 v[28:31], v[170:173], v[194:197], v[28:31]
	v_mfma_f32_16x16x32_bf16 v[24:27], v[178:181], v[194:197], v[24:27]
	v_mfma_f32_16x16x32_bf16 v[12:15], v[170:173], v[202:205], v[12:15]
	v_mfma_f32_16x16x32_bf16 v[8:11], v[178:181], v[202:205], v[8:11]
	v_mfma_f32_16x16x32_bf16 v[4:7], v[170:173], v[212:215], v[4:7]
	v_mfma_f32_16x16x32_bf16 v[0:3], v[178:181], v[212:215], v[0:3]
	s_setprio 0
	s_barrier
	s_add_u32 s2, s2, 0x100
	s_addc_u32 s3, s3, 0
	s_add_u32 s97, s97, 0x100
	s_addc_u32 vcc_lo, vcc_lo, 0
	s_cmp_ge_i32 vcc_hi, s59
	s_mov_b32 s4, vcc_hi
	s_cbranch_scc0 .LBB0_766
	s_and_b64 vcc, exec, s[14:15]
	s_cbranch_vccz .LBB0_769
	s_barrier

; #define PG8_STAGE(bufoff, gbase, voff) do { _Pragma("unroll") for (int _i = 0; _i < 2; ++_i) \
;         __builtin_amdgcn_global_load_lds((const unsigned*)((const char*)(gbase) + (voff)[_i]), (PG8_LAS unsigned*)(lds + (bufoff) + ldsw + _i * 8192), 16, 0, 0); } while (0)
; #define PG8_LDA(dst, b, h) do { if constexpr (FP8) { _Pragma("unroll") for (int m = 0; m < 4; ++m) dst##8[m] = PG8_LD8(lds + PG8_SA(b, h) + aoff + m * 2048); } \
;         else { _Pragma("unroll") for (int m = 0; m < 4; ++m) _Pragma("unroll") for (int k = 0; k < 2; ++k) dst[m][k] = *(const PG8_LAS bf16x8*)(lds + PG8_SA(b, h) + aoff + m * 2048 + k * 1024); } } while (0)
; #define PG8_WAIT_V(n) asm volatile("s_waitcnt vmcnt(" #n ")" ::: "memory")
; #define PG8_WAIT_L(n) asm volatile("s_waitcnt lgkmcnt(" #n ")" ::: "memory")
; #define PG8_BAR __builtin_amdgcn_s_barrier()
; template <class Epi, class Sched, bool ALIGN_EPI = false, bool SP2 = false, bool FP8 = false, bool I8 = false>
; __device__ __forceinline__ void gemm_phase(PG8_LAS unsigned char* lds, const Gemm g, const Sched& S, const Epi& E, const SplitK sk) {
;     ...
;         const bool has_next = S.next(ui + 1, nxt);
;         const char* nA = has_next ? (const char*)g.A + (size_t)nxt.pm * tstep + (size_t)nxt.kt0 * kstep : cA; const char* nB = has_next ? (const char*)g.Bt + (size_t)nxt.pn * tstep + (size_t)nxt.kt0 * kstep : cB;
;         const int nt = cur.nkt;
;         for (int t = 0; t < nt; t += 2) {
;             const bool last = (t == nt - 2);
;             const char* a1 = cA + (size_t)(t + 1) * kstep;
;             const char* a2 = last ? nA : cA + (size_t)(t + 2) * kstep; const char* b2 = last ? nB : cB + (size_t)(t + 2) * kstep;
;             const char* a3 = a2 + kstep; const char* b3 = b2 + kstep;
;             if (last && has_next) S.a_ready(nxt);
;             if constexpr (SP2) {
;             PG8_LDB(B0, 0, 0); PG8_LDB(B1, 0, 1); PG8_SCHED; PG8_LDA(At, 0, 0); PG8_STAGE(PG8_SA(1, 1), a1 + hstep, voffA);
;             PG8_WAIT_V(8); PG8_WAIT_L(0); PG8_BAR; PG8_MMA(0, 0, At, B0); PG8_MMA(0, 1, At, B1); PG8_BAR; PG8_SCHED;
;     ...
; #pragma unroll
;         for (int a = 0; a < 2; ++a)
; #pragma unroll
;             for (int b = 0; b < 2; ++b)
; #pragma unroll
;                 for (int m = 0; m < 4; ++m)
; #pragma unroll
;                     for (int n = 0; n < 2; ++n) acc[a][b][m][n] = (f32x4){0.f, 0.f, 0.f, 0.f};
.LBB0_1062:
	s_ashr_i32 s11, s10, 31
	s_lshl_b64 s[18:19], s[10:11], 20
	s_add_u32 s11, s50, s18
	s_addc_u32 s13, s51, s19
	s_ashr_i32 s15, s14, 31
	s_lshl_b64 s[22:23], s[14:15], 7
	s_add_u32 s18, s11, s22
	s_addc_u32 s19, s13, s23
	s_and_b64 s[40:41], s[16:17], exec
	s_cselect_b32 s11, s19, s21
	s_cselect_b32 s15, s18, s20
	s_ashr_i32 s13, s12, 31
	s_lshl_b64 s[40:41], s[12:13], 20
	s_add_u32 s13, s26, s40
	s_addc_u32 s40, s27, s41
	s_add_u32 s22, s13, s22
	s_addc_u32 s23, s40, s23
	s_and_b64 s[40:41], s[16:17], exec
	s_cselect_b32 s13, s23, s39
	s_cselect_b32 s44, s22, s38
	s_add_i32 s45, s43, -2
	s_add_u32 s20, s20, 0x80080
	s_addc_u32 s21, s21, 0
	s_add_u32 s89, s38, 0x100
	v_mov_b32_e32 v0, 0
	s_addc_u32 s90, s39, 0
	s_mov_b32 s38, 0
	v_mov_b32_e32 v1, v0
	v_mov_b32_e32 v2, v0
	v_mov_b32_e32 v3, v0
	v_mov_b32_e32 v4, v0
	v_mov_b32_e32 v5, v0
	v_mov_b32_e32 v6, v0
	v_mov_b32_e32 v7, v0
	v_mov_b32_e32 v8, v0
	v_mov_b32_e32 v9, v0
	v_mov_b32_e32 v10, v0
	v_mov_b32_e32 v11, v0
	v_mov_b32_e32 v20, v0
	v_mov_b32_e32 v21, v0
	v_mov_b32_e32 v22, v0
	v_mov_b32_e32 v23, v0
	v_mov_b32_e32 v24, v0
	v_mov_b32_e32 v25, v0
	v_mov_b32_e32 v26, v0
	v_mov_b32_e32 v27, v0
	v_mov_b32_e32 v36, v0
	v_mov_b32_e32 v37, v0
	v_mov_b32_e32 v38, v0
	v_mov_b32_e32 v39, v0
	v_mov_b32_e32 v40, v0
	v_mov_b32_e32 v41, v0
	v_mov_b32_e32 v42, v0
	v_mov_b32_e32 v43, v0
	v_mov_b32_e32 v52, v0
	v_mov_b32_e32 v53, v0
	v_mov_b32_e32 v54, v0
	v_mov_b32_e32 v55, v0
	v_mov_b32_e32 v12, v0
	v_mov_b32_e32 v13, v0
	v_mov_b32_e32 v14, v0
	v_mov_b32_e32 v15, v0
	v_mov_b32_e32 v16, v0
	v_mov_b32_e32 v17, v0
	v_mov_b32_e32 v18, v0
	v_mov_b32_e32 v19, v0
	v_mov_b32_e32 v28, v0
	v_mov_b32_e32 v29, v0
	v_mov_b32_e32 v30, v0
	v_mov_b32_e32 v31, v0
	v_mov_b32_e32 v32, v0
	v_mov_b32_e32 v33, v0
	v_mov_b32_e32 v34, v0
	v_mov_b32_e32 v35, v0
	v_mov_b32_e32 v44, v0
	v_mov_b32_e32 v45, v0
	v_mov_b32_e32 v46, v0
	v_mov_b32_e32 v47, v0
	v_mov_b32_e32 v48, v0
	v_mov_b32_e32 v49, v0
	v_mov_b32_e32 v50, v0
	v_mov_b32_e32 v51, v0
	v_mov_b32_e32 v56, v0
	v_mov_b32_e32 v57, v0
	v_mov_b32_e32 v58, v0
	v_mov_b32_e32 v59, v0
	v_mov_b32_e32 v60, v0
	v_mov_b32_e32 v61, v0
	v_mov_b32_e32 v62, v0
	v_mov_b32_e32 v63, v0
	v_mov_b32_e32 v64, v0
	v_mov_b32_e32 v65, v0
	v_mov_b32_e32 v66, v0
	v_mov_b32_e32 v67, v0
	v_mov_b32_e32 v68, v0
	v_mov_b32_e32 v69, v0
	v_mov_b32_e32 v70, v0
	v_mov_b32_e32 v71, v0
	v_mov_b32_e32 v72, v0
	v_mov_b32_e32 v73, v0
	v_mov_b32_e32 v74, v0
	v_mov_b32_e32 v75, v0
	v_mov_b32_e32 v84, v0
	v_mov_b32_e32 v85, v0
	v_mov_b32_e32 v86, v0
	v_mov_b32_e32 v87, v0
	v_mov_b32_e32 v88, v0
	v_mov_b32_e32 v89, v0
	v_mov_b32_e32 v90, v0
	v_mov_b32_e32 v91, v0
	v_mov_b32_e32 v100, v0
	v_mov_b32_e32 v101, v0
	v_mov_b32_e32 v102, v0
	v_mov_b32_e32 v103, v0
	v_mov_b32_e32 v104, v0
	v_mov_b32_e32 v105, v0
	v_mov_b32_e32 v106, v0
	v_mov_b32_e32 v107, v0
	v_mov_b32_e32 v112, v0
	v_mov_b32_e32 v113, v0
	v_mov_b32_e32 v114, v0
	v_mov_b32_e32 v115, v0
	v_mov_b32_e32 v76, v0
	v_mov_b32_e32 v77, v0
	v_mov_b32_e32 v78, v0
	v_mov_b32_e32 v79, v0
	v_mov_b32_e32 v80, v0
	v_mov_b32_e32 v81, v0
	v_mov_b32_e32 v82, v0
	v_mov_b32_e32 v83, v0
	v_mov_b32_e32 v92, v0
	v_mov_b32_e32 v93, v0
	v_mov_b32_e32 v94, v0
	v_mov_b32_e32 v95, v0
	v_mov_b32_e32 v96, v0
	v_mov_b32_e32 v97, v0
	v_mov_b32_e32 v98, v0
	v_mov_b32_e32 v99, v0
	v_mov_b32_e32 v108, v0
	v_mov_b32_e32 v109, v0
	v_mov_b32_e32 v110, v0
	v_mov_b32_e32 v111, v0
	v_mov_b32_e32 v116, v0
	v_mov_b32_e32 v117, v0
	v_mov_b32_e32 v118, v0
	v_mov_b32_e32 v119, v0
	v_mov_b32_e32 v120, v0
	v_mov_b32_e32 v121, v0
	v_mov_b32_e32 v122, v0
	v_mov_b32_e32 v123, v0
	v_mov_b32_e32 v124, v0
	v_mov_b32_e32 v125, v0
	v_mov_b32_e32 v126, v0
	v_mov_b32_e32 v127, v0
.LBB0_1063:
	ds_read_b128 v[140:143], v145
	ds_read_b128 v[148:151], v145 offset:1024
	ds_read_b128 v[152:155], v145 offset:2048
	ds_read_b128 v[156:159], v145 offset:3072
	ds_read_b128 v[160:163], v146
	ds_read_b128 v[164:167], v146 offset:1024
	ds_read_b128 v[168:171], v146 offset:2048
	ds_read_b128 v[172:175], v146 offset:3072
	s_add_i32 s91, s38, 2
	s_add_u32 s39, s20, 0xfff80080
	s_addc_u32 s40, s21, -1
	s_cmp_eq_u32 s45, s38
	s_cselect_b32 s38, s44, s89
	s_cselect_b32 s41, s11, s40
	s_cselect_b32 s40, s15, s39
	s_cselect_b32 s39, s13, s90
	v_lshl_add_u64 v[208:209], s[20:21], 0, v[134:135]
	s_add_i32 m0, s29, 0xc000
	ds_read_b128 v[176:179], v147
	ds_read_b128 v[180:183], v147 offset:1024
	ds_read_b128 v[184:187], v147 offset:2048
	ds_read_b128 v[188:191], v147 offset:3072
	ds_read_b128 v[192:195], v147 offset:4096
	ds_read_b128 v[196:199], v147 offset:5120
	ds_read_b128 v[200:203], v147 offset:6144
	ds_read_b128 v[204:207], v147 offset:7168
	global_load_lds_dwordx4 v[208:209], off
	v_lshl_add_u64 v[208:209], s[20:21], 0, v[136:137]
	s_add_i32 m0, s29, 0xe000
	s_nop 0
	global_load_lds_dwordx4 v[208:209], off
	s_waitcnt vmcnt(8)
	s_waitcnt lgkmcnt(0)
	s_barrier
; #define PG8_STAGE(bufoff, gbase, voff) do { _Pragma("unroll") for (int _i = 0; _i < 2; ++_i) \
;         __builtin_amdgcn_global_load_lds((const unsigned*)((const char*)(gbase) + (voff)[_i]), (PG8_LAS unsigned*)(lds + (bufoff) + ldsw + _i * 8192), 16, 0, 0); } while (0)
; #define PG8_LDA(dst, b, h) do { if constexpr (FP8) { _Pragma("unroll") for (int m = 0; m < 4; ++m) dst##8[m] = PG8_LD8(lds + PG8_SA(b, h) + aoff + m * 2048); } \
;         else { _Pragma("unroll") for (int m = 0; m < 4; ++m) _Pragma("unroll") for (int k = 0; k < 2; ++k) dst[m][k] = *(const PG8_LAS bf16x8*)(lds + PG8_SA(b, h) + aoff + m * 2048 + k * 1024); } } while (0)
; #define PG8_WAIT_V(n) asm volatile("s_waitcnt vmcnt(" #n ")" ::: "memory")
; #define PG8_WAIT_L(n) asm volatile("s_waitcnt lgkmcnt(" #n ")" ::: "memory")
; #define PG8_BAR __builtin_amdgcn_s_barrier()
; #define PG8_SCHED __builtin_amdgcn_sched_barrier(0)
; template <class Epi, class Sched, bool ALIGN_EPI = false, bool SP2 = false, bool FP8 = false, bool I8 = false>
; __device__ __forceinline__ void gemm_phase(PG8_LAS unsigned char* lds, const Gemm g, const Sched& S, const Epi& E, const SplitK sk) {
;     ...
;             PG8_WAIT_V(8); PG8_WAIT_L(0); PG8_BAR; PG8_MMA(0, 0, At, B0); PG8_MMA(0, 1, At, B1); PG8_BAR; PG8_SCHED;
;             PG8_LDA(At, 0, 1); PG8_STAGE(PG8_SB(0, 0), b2, voffB); PG8_STAGE(PG8_SB(0, 1), b2 + hstep, voffB); PG8_STAGE(PG8_SA(0, 0), a2, voffA);
;             PG8_WAIT_V(8); PG8_WAIT_L(0); PG8_BAR; PG8_MMA(1, 0, At, B0); PG8_MMA(1, 1, At, B1); PG8_BAR; PG8_SCHED;
	s_setprio 1
	s_waitcnt lgkmcnt(0)
	v_mfma_f32_16x16x32_bf16 v[124:127], v[140:143], v[176:179], v[124:127]
	v_mfma_f32_16x16x32_bf16 v[120:123], v[152:155], v[176:179], v[120:123]
	v_mfma_f32_16x16x32_bf16 v[116:119], v[140:143], v[184:187], v[116:119]
	v_mfma_f32_16x16x32_bf16 v[108:111], v[152:155], v[184:187], v[108:111]
	v_mfma_f32_16x16x32_bf16 v[96:99], v[140:143], v[192:195], v[96:99]
	v_mfma_f32_16x16x32_bf16 v[92:95], v[152:155], v[192:195], v[92:95]
	v_mfma_f32_16x16x32_bf16 v[80:83], v[140:143], v[200:203], v[80:83]
	v_mfma_f32_16x16x32_bf16 v[76:79], v[152:155], v[200:203], v[76:79]
	v_mfma_f32_16x16x32_bf16 v[124:127], v[148:151], v[180:183], v[124:127]
	v_mfma_f32_16x16x32_bf16 v[120:123], v[156:159], v[180:183], v[120:123]
	v_mfma_f32_16x16x32_bf16 v[116:119], v[148:151], v[188:191], v[116:119]
	v_mfma_f32_16x16x32_bf16 v[108:111], v[156:159], v[188:191], v[108:111]
	v_mfma_f32_16x16x32_bf16 v[96:99], v[148:151], v[196:199], v[96:99]
	v_mfma_f32_16x16x32_bf16 v[92:95], v[156:159], v[196:199], v[92:95]
	v_mfma_f32_16x16x32_bf16 v[80:83], v[148:151], v[204:207], v[80:83]
	v_mfma_f32_16x16x32_bf16 v[76:79], v[156:159], v[204:207], v[76:79]
	s_setprio 0
	s_setprio 1
	v_mfma_f32_16x16x32_bf16 v[112:115], v[160:163], v[176:179], v[112:115]
	v_mfma_f32_16x16x32_bf16 v[104:107], v[168:171], v[176:179], v[104:107]
	v_mfma_f32_16x16x32_bf16 v[100:103], v[160:163], v[184:187], v[100:103]
	v_mfma_f32_16x16x32_bf16 v[88:91], v[168:171], v[184:187], v[88:91]
	v_mfma_f32_16x16x32_bf16 v[84:87], v[160:163], v[192:195], v[84:87]
	v_mfma_f32_16x16x32_bf16 v[72:75], v[168:171], v[192:195], v[72:75]
	v_mfma_f32_16x16x32_bf16 v[68:71], v[160:163], v[200:203], v[68:71]
	v_mfma_f32_16x16x32_bf16 v[64:67], v[168:171], v[200:203], v[64:67]
	v_mfma_f32_16x16x32_bf16 v[112:115], v[164:167], v[180:183], v[112:115]
	v_mfma_f32_16x16x32_bf16 v[104:107], v[172:175], v[180:183], v[104:107]
	v_mfma_f32_16x16x32_bf16 v[100:103], v[164:167], v[188:191], v[100:103]
	v_mfma_f32_16x16x32_bf16 v[88:91], v[172:175], v[188:191], v[88:91]
	v_mfma_f32_16x16x32_bf16 v[84:87], v[164:167], v[196:199], v[84:87]
	v_mfma_f32_16x16x32_bf16 v[72:75], v[172:175], v[196:199], v[72:75]
	v_mfma_f32_16x16x32_bf16 v[68:71], v[164:167], v[204:207], v[68:71]
	v_mfma_f32_16x16x32_bf16 v[64:67], v[172:175], v[204:207], v[64:67]
	s_setprio 0
	s_barrier
	s_add_i32 s92, s79, s28
	v_lshl_add_u64 v[208:209], s[38:39], 0, v[128:129]
	s_mov_b32 m0, s92
	ds_read_b128 v[176:179], v147 offset:16384
	ds_read_b128 v[180:183], v147 offset:17408
	ds_read_b128 v[184:187], v147 offset:18432
	ds_read_b128 v[188:191], v147 offset:19456
	ds_read_b128 v[192:195], v147 offset:20480
	ds_read_b128 v[196:199], v147 offset:21504
	ds_read_b128 v[200:203], v147 offset:22528
	ds_read_b128 v[204:207], v147 offset:23552
	global_load_lds_dwordx4 v[208:209], off
	s_add_i32 m0, s92, 0x2000
	s_add_u32 s92, s38, 0x80000
	v_lshl_add_u64 v[212:213], s[38:39], 0, v[130:131]
	s_addc_u32 s93, s39, 0
	s_add_i32 s94, s80, s28
	global_load_lds_dwordx4 v[212:213], off
	v_lshl_add_u64 v[214:215], s[92:93], 0, v[128:129]
	s_mov_b32 m0, s94
	v_lshl_add_u64 v[216:217], s[40:41], 0, v[130:131]
	global_load_lds_dwordx4 v[214:215], off
	v_lshl_add_u64 v[214:215], s[92:93], 0, v[130:131]
	s_add_i32 m0, s94, 0x2000
	s_nop 0
	global_load_lds_dwordx4 v[214:215], off
	v_lshl_add_u64 v[214:215], s[40:41], 0, v[128:129]
	s_mov_b32 m0, s29
	s_nop 0
	global_load_lds_dwordx4 v[214:215], off
	s_mov_b32 m0, s30
	s_nop 0
	global_load_lds_dwordx4 v[216:217], off
	s_waitcnt vmcnt(8)
	s_waitcnt lgkmcnt(0)
	s_barrier
	s_setprio 1
	s_waitcnt lgkmcnt(0)
	v_mfma_f32_16x16x32_bf16 v[60:63], v[140:143], v[176:179], v[60:63]
	v_mfma_f32_16x16x32_bf16 v[56:59], v[152:155], v[176:179], v[56:59]
	v_mfma_f32_16x16x32_bf16 v[48:51], v[140:143], v[184:187], v[48:51]
	v_mfma_f32_16x16x32_bf16 v[44:47], v[152:155], v[184:187], v[44:47]
	v_mfma_f32_16x16x32_bf16 v[32:35], v[140:143], v[192:195], v[32:35]
	v_mfma_f32_16x16x32_bf16 v[28:31], v[152:155], v[192:195], v[28:31]
	v_mfma_f32_16x16x32_bf16 v[16:19], v[140:143], v[200:203], v[16:19]
	v_mfma_f32_16x16x32_bf16 v[12:15], v[152:155], v[200:203], v[12:15]
	v_mfma_f32_16x16x32_bf16 v[60:63], v[148:151], v[180:183], v[60:63]
	v_mfma_f32_16x16x32_bf16 v[56:59], v[156:159], v[180:183], v[56:59]
	v_mfma_f32_16x16x32_bf16 v[48:51], v[148:151], v[188:191], v[48:51]
	v_mfma_f32_16x16x32_bf16 v[44:47], v[156:159], v[188:191], v[44:47]
	v_mfma_f32_16x16x32_bf16 v[32:35], v[148:151], v[196:199], v[32:35]
	v_mfma_f32_16x16x32_bf16 v[28:31], v[156:159], v[196:199], v[28:31]
	v_mfma_f32_16x16x32_bf16 v[16:19], v[148:151], v[204:207], v[16:19]
	v_mfma_f32_16x16x32_bf16 v[12:15], v[156:159], v[204:207], v[12:15]
	s_setprio 0
	s_setprio 1
	v_mfma_f32_16x16x32_bf16 v[52:55], v[160:163], v[176:179], v[52:55]
	v_mfma_f32_16x16x32_bf16 v[40:43], v[168:171], v[176:179], v[40:43]
	v_mfma_f32_16x16x32_bf16 v[36:39], v[160:163], v[184:187], v[36:39]
	v_mfma_f32_16x16x32_bf16 v[24:27], v[168:171], v[184:187], v[24:27]
	v_mfma_f32_16x16x32_bf16 v[20:23], v[160:163], v[192:195], v[20:23]
	v_mfma_f32_16x16x32_bf16 v[8:11], v[168:171], v[192:195], v[8:11]
	v_mfma_f32_16x16x32_bf16 v[4:7], v[160:163], v[200:203], v[4:7]
	v_mfma_f32_16x16x32_bf16 v[0:3], v[168:171], v[200:203], v[0:3]
	v_mfma_f32_16x16x32_bf16 v[52:55], v[164:167], v[180:183], v[52:55]
	v_mfma_f32_16x16x32_bf16 v[40:43], v[172:175], v[180:183], v[40:43]
	v_mfma_f32_16x16x32_bf16 v[36:39], v[164:167], v[188:191], v[36:39]
	v_mfma_f32_16x16x32_bf16 v[24:27], v[172:175], v[188:191], v[24:27]
	v_mfma_f32_16x16x32_bf16 v[20:23], v[164:167], v[196:199], v[20:23]
	v_mfma_f32_16x16x32_bf16 v[8:11], v[172:175], v[196:199], v[8:11]
	v_mfma_f32_16x16x32_bf16 v[4:7], v[164:167], v[204:207], v[4:7]
	v_mfma_f32_16x16x32_bf16 v[0:3], v[172:175], v[204:207], v[0:3]
	s_setprio 0
	s_barrier
; #define PG8_STAGE(bufoff, gbase, voff) do { _Pragma("unroll") for (int _i = 0; _i < 2; ++_i) \
;         __builtin_amdgcn_global_load_lds((const unsigned*)((const char*)(gbase) + (voff)[_i]), (PG8_LAS unsigned*)(lds + (bufoff) + ldsw + _i * 8192), 16, 0, 0); } while (0)
; #define PG8_LDA(dst, b, h) do { if constexpr (FP8) { _Pragma("unroll") for (int m = 0; m < 4; ++m) dst##8[m] = PG8_LD8(lds + PG8_SA(b, h) + aoff + m * 2048); } \
;         else { _Pragma("unroll") for (int m = 0; m < 4; ++m) _Pragma("unroll") for (int k = 0; k < 2; ++k) dst[m][k] = *(const PG8_LAS bf16x8*)(lds + PG8_SA(b, h) + aoff + m * 2048 + k * 1024); } } while (0)
; #define PG8_LDB(dst, b, h) do { if constexpr (FP8) { _Pragma("unroll") for (int n = 0; n < 2; ++n) dst##8[n] = PG8_LD8(lds + PG8_SB(b, h) + boff + n * 2048); } \
;         else { _Pragma("unroll") for (int n = 0; n < 2; ++n) _Pragma("unroll") for (int k = 0; k < 2; ++k) dst[n][k] = *(const PG8_LAS bf16x8*)(lds + PG8_SB(b, h) + boff + n * 2048 + k * 1024); } } while (0)
; #define PG8_WAIT_V(n) asm volatile("s_waitcnt vmcnt(" #n ")" ::: "memory")
; #define PG8_WAIT_L(n) asm volatile("s_waitcnt lgkmcnt(" #n ")" ::: "memory")
; #define PG8_BAR __builtin_amdgcn_s_barrier()
; #define PG8_SCHED __builtin_amdgcn_sched_barrier(0)
; template <class Epi, class Sched, bool ALIGN_EPI = false, bool SP2 = false, bool FP8 = false, bool I8 = false>
; __device__ __forceinline__ void gemm_phase(PG8_LAS unsigned char* lds, const Gemm g, const Sched& S, const Epi& E, const SplitK sk) {
;     ...
;             PG8_LDB(B0, 1, 0); PG8_LDB(B1, 1, 1); PG8_SCHED; PG8_LDA(At, 1, 0); PG8_STAGE(PG8_SA(0, 1), a2 + hstep, voffA);
;             PG8_WAIT_V(8); PG8_WAIT_L(0); PG8_BAR; PG8_MMA(0, 0, At, B0); PG8_MMA(0, 1, At, B1); PG8_BAR; PG8_SCHED;
	s_add_i32 s92, 0, 0x18000
	v_add_u32_e32 v132, s92, v144
	s_add_i32 s93, 0, 0x1c000
	ds_read_b128 v[140:143], v132
	ds_read_b128 v[148:151], v132 offset:1024
	ds_read_b128 v[152:155], v132 offset:2048
	ds_read_b128 v[156:159], v132 offset:3072
	v_add_u32_e32 v132, s93, v144
	ds_read_b128 v[160:163], v132
	ds_read_b128 v[164:167], v132 offset:1024
	ds_read_b128 v[168:171], v132 offset:2048
	ds_read_b128 v[172:175], v132 offset:3072
	s_add_u32 s40, s40, 0x80000
	s_addc_u32 s41, s41, 0
	s_mov_b32 m0, s31
	v_lshl_add_u64 v[218:219], s[40:41], 0, v[128:129]
	ds_read_b128 v[176:179], v147 offset:32768
	ds_read_b128 v[180:183], v147 offset:33792
	ds_read_b128 v[184:187], v147 offset:34816
	ds_read_b128 v[188:191], v147 offset:35840
	ds_read_b128 v[192:195], v147 offset:36864
	ds_read_b128 v[196:199], v147 offset:37888
	ds_read_b128 v[200:203], v147 offset:38912
	ds_read_b128 v[204:207], v147 offset:39936
	global_load_lds_dwordx4 v[218:219], off
	v_lshl_add_u64 v[218:219], s[40:41], 0, v[130:131]
	s_mov_b32 m0, s33
	s_nop 0
	global_load_lds_dwordx4 v[218:219], off
	s_waitcnt vmcnt(8)
	s_waitcnt lgkmcnt(0)
	s_barrier
	s_setprio 1
	s_waitcnt lgkmcnt(0)
	v_mfma_f32_16x16x32_bf16 v[124:127], v[140:143], v[176:179], v[124:127]
	v_mfma_f32_16x16x32_bf16 v[120:123], v[152:155], v[176:179], v[120:123]
	v_mfma_f32_16x16x32_bf16 v[116:119], v[140:143], v[184:187], v[116:119]
	v_mfma_f32_16x16x32_bf16 v[108:111], v[152:155], v[184:187], v[108:111]
	v_mfma_f32_16x16x32_bf16 v[96:99], v[140:143], v[192:195], v[96:99]
	v_mfma_f32_16x16x32_bf16 v[92:95], v[152:155], v[192:195], v[92:95]
	v_mfma_f32_16x16x32_bf16 v[80:83], v[140:143], v[200:203], v[80:83]
	v_mfma_f32_16x16x32_bf16 v[76:79], v[152:155], v[200:203], v[76:79]
	v_mfma_f32_16x16x32_bf16 v[124:127], v[148:151], v[180:183], v[124:127]
	v_mfma_f32_16x16x32_bf16 v[120:123], v[156:159], v[180:183], v[120:123]
	v_mfma_f32_16x16x32_bf16 v[116:119], v[148:151], v[188:191], v[116:119]
	v_mfma_f32_16x16x32_bf16 v[108:111], v[156:159], v[188:191], v[108:111]
	v_mfma_f32_16x16x32_bf16 v[96:99], v[148:151], v[196:199], v[96:99]
	v_mfma_f32_16x16x32_bf16 v[92:95], v[156:159], v[196:199], v[92:95]
	v_mfma_f32_16x16x32_bf16 v[80:83], v[148:151], v[204:207], v[80:83]
	v_mfma_f32_16x16x32_bf16 v[76:79], v[156:159], v[204:207], v[76:79]
	s_setprio 0
	s_setprio 1
	v_mfma_f32_16x16x32_bf16 v[112:115], v[160:163], v[176:179], v[112:115]
	v_mfma_f32_16x16x32_bf16 v[104:107], v[168:171], v[176:179], v[104:107]
	v_mfma_f32_16x16x32_bf16 v[100:103], v[160:163], v[184:187], v[100:103]
	v_mfma_f32_16x16x32_bf16 v[88:91], v[168:171], v[184:187], v[88:91]
	v_mfma_f32_16x16x32_bf16 v[84:87], v[160:163], v[192:195], v[84:87]
	v_mfma_f32_16x16x32_bf16 v[72:75], v[168:171], v[192:195], v[72:75]
	v_mfma_f32_16x16x32_bf16 v[68:71], v[160:163], v[200:203], v[68:71]
	v_mfma_f32_16x16x32_bf16 v[64:67], v[168:171], v[200:203], v[64:67]
	v_mfma_f32_16x16x32_bf16 v[112:115], v[164:167], v[180:183], v[112:115]
	v_mfma_f32_16x16x32_bf16 v[104:107], v[172:175], v[180:183], v[104:107]
	v_mfma_f32_16x16x32_bf16 v[100:103], v[164:167], v[188:191], v[100:103]
	v_mfma_f32_16x16x32_bf16 v[88:91], v[172:175], v[188:191], v[88:91]
	v_mfma_f32_16x16x32_bf16 v[84:87], v[164:167], v[196:199], v[84:87]
	v_mfma_f32_16x16x32_bf16 v[72:75], v[172:175], v[196:199], v[72:75]
	v_mfma_f32_16x16x32_bf16 v[68:71], v[164:167], v[204:207], v[68:71]
	v_mfma_f32_16x16x32_bf16 v[64:67], v[172:175], v[204:207], v[64:67]
	s_setprio 0
	s_barrier
; #define PG8_STAGE(bufoff, gbase, voff) do { _Pragma("unroll") for (int _i = 0; _i < 2; ++_i) \
;         __builtin_amdgcn_global_load_lds((const unsigned*)((const char*)(gbase) + (voff)[_i]), (PG8_LAS unsigned*)(lds + (bufoff) + ldsw + _i * 8192), 16, 0, 0); } while (0)
; #define PG8_LDA(dst, b, h) do { if constexpr (FP8) { _Pragma("unroll") for (int m = 0; m < 4; ++m) dst##8[m] = PG8_LD8(lds + PG8_SA(b, h) + aoff + m * 2048); } \
;         else { _Pragma("unroll") for (int m = 0; m < 4; ++m) _Pragma("unroll") for (int k = 0; k < 2; ++k) dst[m][k] = *(const PG8_LAS bf16x8*)(lds + PG8_SA(b, h) + aoff + m * 2048 + k * 1024); } } while (0)
; #define PG8_WAIT_V(n) asm volatile("s_waitcnt vmcnt(" #n ")" ::: "memory")
; #define PG8_WAIT_L(n) asm volatile("s_waitcnt lgkmcnt(" #n ")" ::: "memory")
; #define PG8_BAR __builtin_amdgcn_s_barrier()
; #define PG8_SCHED __builtin_amdgcn_sched_barrier(0)
; template <class Epi, class Sched, bool ALIGN_EPI = false, bool SP2 = false, bool FP8 = false, bool I8 = false>
; __device__ __forceinline__ void gemm_phase(PG8_LAS unsigned char* lds, const Gemm g, const Sched& S, const Epi& E, const SplitK sk) {
;     ...
;             PG8_LDA(At, 1, 1); PG8_STAGE(PG8_SB(1, 0), b3, voffB); PG8_STAGE(PG8_SB(1, 1), b3 + hstep, voffB); PG8_STAGE(PG8_SA(1, 0), a3, voffA);
;             PG8_WAIT_V(8); PG8_WAIT_L(0); PG8_BAR; PG8_MMA(1, 0, At, B0); PG8_MMA(1, 1, At, B1); PG8_BAR; PG8_SCHED;
;     ...
;         if constexpr (ALIGN_EPI) { if (wr == 0) PG8_BAR; }
	s_add_i32 s40, s92, s28
	v_lshl_add_u64 v[208:209], v[208:209], 0, s[4:5]
	s_mov_b32 m0, s40
	ds_read_b128 v[176:179], v147 offset:49152
	ds_read_b128 v[180:183], v147 offset:50176
	ds_read_b128 v[184:187], v147 offset:51200
	ds_read_b128 v[188:191], v147 offset:52224
	ds_read_b128 v[192:195], v147 offset:53248
	ds_read_b128 v[196:199], v147 offset:54272
	ds_read_b128 v[200:203], v147 offset:55296
	ds_read_b128 v[204:207], v147 offset:56320
	global_load_lds_dwordx4 v[208:209], off
	s_add_i32 m0, s40, 0x2000
	s_add_u32 s38, s38, 0x80080
	v_lshl_add_u64 v[208:209], v[212:213], 0, s[4:5]
	s_addc_u32 s39, s39, 0
	s_add_i32 s40, s93, s28
	global_load_lds_dwordx4 v[208:209], off
	v_lshl_add_u64 v[208:209], s[38:39], 0, v[128:129]
	s_mov_b32 m0, s40
	s_nop 0
	global_load_lds_dwordx4 v[208:209], off
	v_lshl_add_u64 v[208:209], s[38:39], 0, v[130:131]
	s_add_i32 m0, s40, 0x2000
	s_nop 0
	global_load_lds_dwordx4 v[208:209], off
	v_lshl_add_u64 v[208:209], v[214:215], 0, s[4:5]
	s_mov_b32 m0, s62
	s_nop 0
	global_load_lds_dwordx4 v[208:209], off
	v_lshl_add_u64 v[208:209], v[216:217], 0, s[4:5]
	s_mov_b32 m0, s63
	s_nop 0
	global_load_lds_dwordx4 v[208:209], off
	s_waitcnt vmcnt(8)
	s_waitcnt lgkmcnt(0)
	s_barrier
	s_setprio 1
	s_waitcnt lgkmcnt(0)
	v_mfma_f32_16x16x32_bf16 v[60:63], v[140:143], v[176:179], v[60:63]
	v_mfma_f32_16x16x32_bf16 v[56:59], v[152:155], v[176:179], v[56:59]
	v_mfma_f32_16x16x32_bf16 v[48:51], v[140:143], v[184:187], v[48:51]
	v_mfma_f32_16x16x32_bf16 v[44:47], v[152:155], v[184:187], v[44:47]
	v_mfma_f32_16x16x32_bf16 v[32:35], v[140:143], v[192:195], v[32:35]
	v_mfma_f32_16x16x32_bf16 v[28:31], v[152:155], v[192:195], v[28:31]
	v_mfma_f32_16x16x32_bf16 v[16:19], v[140:143], v[200:203], v[16:19]
	v_mfma_f32_16x16x32_bf16 v[12:15], v[152:155], v[200:203], v[12:15]
	v_mfma_f32_16x16x32_bf16 v[60:63], v[148:151], v[180:183], v[60:63]
	v_mfma_f32_16x16x32_bf16 v[56:59], v[156:159], v[180:183], v[56:59]
	v_mfma_f32_16x16x32_bf16 v[48:51], v[148:151], v[188:191], v[48:51]
	v_mfma_f32_16x16x32_bf16 v[44:47], v[156:159], v[188:191], v[44:47]
	v_mfma_f32_16x16x32_bf16 v[32:35], v[148:151], v[196:199], v[32:35]
	v_mfma_f32_16x16x32_bf16 v[28:31], v[156:159], v[196:199], v[28:31]
	v_mfma_f32_16x16x32_bf16 v[16:19], v[148:151], v[204:207], v[16:19]
	v_mfma_f32_16x16x32_bf16 v[12:15], v[156:159], v[204:207], v[12:15]
	s_setprio 0
	s_setprio 1
	v_mfma_f32_16x16x32_bf16 v[52:55], v[160:163], v[176:179], v[52:55]
	v_mfma_f32_16x16x32_bf16 v[40:43], v[168:171], v[176:179], v[40:43]
	v_mfma_f32_16x16x32_bf16 v[36:39], v[160:163], v[184:187], v[36:39]
	v_mfma_f32_16x16x32_bf16 v[24:27], v[168:171], v[184:187], v[24:27]
	v_mfma_f32_16x16x32_bf16 v[20:23], v[160:163], v[192:195], v[20:23]
	v_mfma_f32_16x16x32_bf16 v[8:11], v[168:171], v[192:195], v[8:11]
	v_mfma_f32_16x16x32_bf16 v[4:7], v[160:163], v[200:203], v[4:7]
	v_mfma_f32_16x16x32_bf16 v[0:3], v[168:171], v[200:203], v[0:3]
	v_mfma_f32_16x16x32_bf16 v[52:55], v[164:167], v[180:183], v[52:55]
	v_mfma_f32_16x16x32_bf16 v[40:43], v[172:175], v[180:183], v[40:43]
	v_mfma_f32_16x16x32_bf16 v[36:39], v[164:167], v[188:191], v[36:39]
	v_mfma_f32_16x16x32_bf16 v[24:27], v[172:175], v[188:191], v[24:27]
	v_mfma_f32_16x16x32_bf16 v[20:23], v[164:167], v[196:199], v[20:23]
	v_mfma_f32_16x16x32_bf16 v[8:11], v[172:175], v[196:199], v[8:11]
	v_mfma_f32_16x16x32_bf16 v[4:7], v[164:167], v[204:207], v[4:7]
	v_mfma_f32_16x16x32_bf16 v[0:3], v[172:175], v[204:207], v[0:3]
	s_setprio 0
	s_barrier
	s_add_u32 s20, s20, 0x100
	s_addc_u32 s21, s21, 0
	s_add_u32 s89, s89, 0x100
	s_addc_u32 s90, s90, 0
	s_cmp_ge_i32 s91, s43
	s_mov_b32 s38, s91
	s_cbranch_scc0 .LBB0_1063
	s_and_b64 vcc, exec, s[6:7]
	s_cbranch_vccz .LBB0_1066
	s_barrier

; #define PG8_STAGE(bufoff, gbase, voff) do { _Pragma("unroll") for (int _i = 0; _i < 2; ++_i) \
;         __builtin_amdgcn_global_load_lds((const unsigned*)((const char*)(gbase) + (voff)[_i]), (PG8_LAS unsigned*)(lds + (bufoff) + ldsw + _i * 8192), 16, 0, 0); } while (0)
; #define PG8_LDA(dst, b, h) do { if constexpr (FP8) { _Pragma("unroll") for (int m = 0; m < 4; ++m) dst##8[m] = PG8_LD8(lds + PG8_SA(b, h) + aoff + m * 2048); } \
;         else { _Pragma("unroll") for (int m = 0; m < 4; ++m) _Pragma("unroll") for (int k = 0; k < 2; ++k) dst[m][k] = *(const PG8_LAS bf16x8*)(lds + PG8_SA(b, h) + aoff + m * 2048 + k * 1024); } } while (0)
; #define PG8_WAIT_V(n) asm volatile("s_waitcnt vmcnt(" #n ")" ::: "memory")
; #define PG8_WAIT_L(n) asm volatile("s_waitcnt lgkmcnt(" #n ")" ::: "memory")
; template <class Epi, class Sched, bool ALIGN_EPI = false, bool SP2 = false, bool FP8 = false, bool I8 = false>
; __device__ __forceinline__ void gemm_phase(PG8_LAS unsigned char* lds, const Gemm g, const Sched& S, const Epi& E, const SplitK sk) {
;     ...
;         if constexpr (Epi::HAS_PRE) E.pre(cur, wr, epre);
;         const bool has_next = S.next(ui + 1, nxt);
;         const char* nA = has_next ? (const char*)g.A + (size_t)nxt.pm * tstep + (size_t)nxt.kt0 * kstep : cA; const char* nB = has_next ? (const char*)g.Bt + (size_t)nxt.pn * tstep + (size_t)nxt.kt0 * kstep : cB;
;         const int nt = cur.nkt;
;         for (int t = 0; t < nt; t += 2) {
;             const bool last = (t == nt - 2);
;             const char* a1 = cA + (size_t)(t + 1) * kstep;
;             const char* a2 = last ? nA : cA + (size_t)(t + 2) * kstep; const char* b2 = last ? nB : cB + (size_t)(t + 2) * kstep;
;             const char* a3 = a2 + kstep; const char* b3 = b2 + kstep;
;             if (last && has_next) S.a_ready(nxt);
;             if constexpr (SP2) {
;             PG8_LDB(B0, 0, 0); PG8_LDB(B1, 0, 1); PG8_SCHED; PG8_LDA(At, 0, 0); PG8_STAGE(PG8_SA(1, 1), a1 + hstep, voffA);
;             PG8_WAIT_V(8); PG8_WAIT_L(0); PG8_BAR; PG8_MMA(0, 0, At, B0); PG8_MMA(0, 1, At, B1); PG8_BAR; PG8_SCHED;
;     ...
; #pragma unroll
;         for (int a = 0; a < 2; ++a)
; #pragma unroll
;             for (int b = 0; b < 2; ++b)
; #pragma unroll
;                 for (int m = 0; m < 4; ++m)
; #pragma unroll
;                     for (int n = 0; n < 2; ++n) acc[a][b][m][n] = (f32x4){0.f, 0.f, 0.f, 0.f};
.LBB0_1222:
	s_ashr_i32 s3, s2, 31
	s_lshl_b64 s[22:23], s[2:3], 19
	s_add_u32 s3, s50, s22
	s_addc_u32 s15, s51, s23
	s_ashr_i32 s17, s16, 31
	s_lshl_b64 s[34:35], s[16:17], 7
	s_add_u32 s22, s3, s34
	s_addc_u32 s23, s15, s35
	s_and_b64 s[40:41], s[18:19], exec
	s_cselect_b32 s3, s23, s21
	s_cselect_b32 s17, s22, s20
	s_ashr_i32 s15, s14, 31
	s_lshl_b64 s[40:41], s[14:15], 19
	s_add_u32 s15, s26, s40
	s_addc_u32 s40, s27, s41
	s_add_u32 s34, s15, s34
	s_addc_u32 s35, s40, s35
	s_and_b64 s[40:41], s[18:19], exec
	s_cselect_b32 s15, s35, s39
	s_cselect_b32 s44, s34, s38
	s_add_i32 s45, s43, -2
	s_add_u32 s20, s20, 0x40080
	s_addc_u32 s21, s21, 0
	s_add_u32 s75, s38, 0x100
	s_addc_u32 s76, s39, 0
	s_mov_b32 s38, 0
	v_mov_b32_e32 v0, 0
	v_mov_b32_e32 v1, 0
	v_mov_b32_e32 v2, 0
	v_mov_b32_e32 v3, 0
	v_mov_b32_e32 v8, 0
	v_mov_b32_e32 v9, 0
	v_mov_b32_e32 v10, 0
	v_mov_b32_e32 v11, 0
	v_mov_b32_e32 v16, 0
	v_mov_b32_e32 v17, 0
	v_mov_b32_e32 v18, 0
	v_mov_b32_e32 v19, 0
	v_mov_b32_e32 v24, 0
	v_mov_b32_e32 v25, 0
	v_mov_b32_e32 v26, 0
	v_mov_b32_e32 v27, 0
	v_mov_b32_e32 v32, 0
	v_mov_b32_e32 v33, 0
	v_mov_b32_e32 v34, 0
	v_mov_b32_e32 v35, 0
	v_mov_b32_e32 v40, 0
	v_mov_b32_e32 v41, 0
	v_mov_b32_e32 v42, 0
	v_mov_b32_e32 v43, 0
	v_mov_b32_e32 v48, 0
	v_mov_b32_e32 v49, 0
	v_mov_b32_e32 v50, 0
	v_mov_b32_e32 v51, 0
	v_mov_b32_e32 v56, 0
	v_mov_b32_e32 v57, 0
	v_mov_b32_e32 v58, 0
	v_mov_b32_e32 v59, 0
	v_mov_b32_e32 v4, 0
	v_mov_b32_e32 v5, 0
	v_mov_b32_e32 v6, 0
	v_mov_b32_e32 v7, 0
	v_mov_b32_e32 v12, 0
	v_mov_b32_e32 v13, 0
	v_mov_b32_e32 v14, 0
	v_mov_b32_e32 v15, 0
	v_mov_b32_e32 v20, 0
	v_mov_b32_e32 v21, 0
	v_mov_b32_e32 v22, 0
	v_mov_b32_e32 v23, 0
	v_mov_b32_e32 v28, 0
	v_mov_b32_e32 v29, 0
	v_mov_b32_e32 v30, 0
	v_mov_b32_e32 v31, 0
	v_mov_b32_e32 v36, 0
	v_mov_b32_e32 v37, 0
	v_mov_b32_e32 v38, 0
	v_mov_b32_e32 v39, 0
	v_mov_b32_e32 v44, 0
	v_mov_b32_e32 v45, 0
	v_mov_b32_e32 v46, 0
	v_mov_b32_e32 v47, 0
	v_mov_b32_e32 v52, 0
	v_mov_b32_e32 v53, 0
	v_mov_b32_e32 v54, 0
	v_mov_b32_e32 v55, 0
	v_mov_b32_e32 v60, 0
	v_mov_b32_e32 v61, 0
	v_mov_b32_e32 v62, 0
	v_mov_b32_e32 v63, 0
	v_mov_b32_e32 v64, 0
	v_mov_b32_e32 v65, 0
	v_mov_b32_e32 v66, 0
	v_mov_b32_e32 v67, 0
	v_mov_b32_e32 v72, 0
	v_mov_b32_e32 v73, 0
	v_mov_b32_e32 v74, 0
	v_mov_b32_e32 v75, 0
	v_mov_b32_e32 v80, 0
	v_mov_b32_e32 v81, 0
	v_mov_b32_e32 v82, 0
	v_mov_b32_e32 v83, 0
	v_mov_b32_e32 v88, 0
	v_mov_b32_e32 v89, 0
	v_mov_b32_e32 v90, 0
	v_mov_b32_e32 v91, 0
	v_mov_b32_e32 v96, 0
	v_mov_b32_e32 v97, 0
	v_mov_b32_e32 v98, 0
	v_mov_b32_e32 v99, 0
	v_mov_b32_e32 v104, 0
	v_mov_b32_e32 v105, 0
	v_mov_b32_e32 v106, 0
	v_mov_b32_e32 v107, 0
	v_mov_b32_e32 v112, 0
	v_mov_b32_e32 v113, 0
	v_mov_b32_e32 v114, 0
	v_mov_b32_e32 v115, 0
	v_mov_b32_e32 v120, 0
	v_mov_b32_e32 v121, 0
	v_mov_b32_e32 v122, 0
	v_mov_b32_e32 v123, 0
	v_mov_b32_e32 v68, 0
	v_mov_b32_e32 v69, 0
	v_mov_b32_e32 v70, 0
	v_mov_b32_e32 v71, 0
	v_mov_b32_e32 v76, 0
	v_mov_b32_e32 v77, 0
	v_mov_b32_e32 v78, 0
	v_mov_b32_e32 v79, 0
	v_mov_b32_e32 v84, 0
	v_mov_b32_e32 v85, 0
	v_mov_b32_e32 v86, 0
	v_mov_b32_e32 v87, 0
	v_mov_b32_e32 v92, 0
	v_mov_b32_e32 v93, 0
	v_mov_b32_e32 v94, 0
	v_mov_b32_e32 v95, 0
	v_mov_b32_e32 v100, 0
	v_mov_b32_e32 v101, 0
	v_mov_b32_e32 v102, 0
	v_mov_b32_e32 v103, 0
	v_mov_b32_e32 v108, 0
	v_mov_b32_e32 v109, 0
	v_mov_b32_e32 v110, 0
	v_mov_b32_e32 v111, 0
	v_mov_b32_e32 v116, 0
	v_mov_b32_e32 v117, 0
	v_mov_b32_e32 v118, 0
	v_mov_b32_e32 v119, 0
	v_mov_b32_e32 v124, 0
	v_mov_b32_e32 v125, 0
	v_mov_b32_e32 v126, 0
	v_mov_b32_e32 v127, 0
.LBB0_1223:
	v_add_u32_e32 v136, s63, v148
	ds_read_b128 v[158:161], v136
	ds_read_b128 v[162:165], v136 offset:1024
	ds_read_b128 v[166:169], v136 offset:2048
	ds_read_b128 v[170:173], v136 offset:3072
	v_add_u32_e32 v136, s64, v148
	ds_read_b128 v[174:177], v136
	ds_read_b128 v[178:181], v136 offset:1024
	ds_read_b128 v[182:185], v136 offset:2048
	ds_read_b128 v[186:189], v136 offset:3072
	s_add_i32 s77, s38, 2
	s_add_u32 s39, s20, 0xfffc0080
	s_addc_u32 s40, s21, -1
	s_cmp_eq_u32 s45, s38
	s_cselect_b32 s38, s44, s75
	s_cselect_b32 s41, s3, s40
	s_cselect_b32 s40, s17, s39
	s_cselect_b32 s39, s15, s76
	v_lshl_add_u64 v[144:145], s[20:21], 0, v[138:139]
	s_add_i32 m0, s29, 0xc000
	ds_read_b128 v[190:193], v149
	ds_read_b128 v[194:197], v149 offset:1024
	ds_read_b128 v[198:201], v149 offset:2048
	ds_read_b128 v[202:205], v149 offset:3072
	ds_read_b128 v[206:209], v149 offset:4096
	ds_read_b128 v[212:215], v149 offset:5120
	ds_read_b128 v[216:219], v149 offset:6144
	ds_read_b128 v[220:223], v149 offset:7168
	global_load_lds_dwordx4 v[144:145], off
	v_lshl_add_u64 v[144:145], s[20:21], 0, v[140:141]
	s_add_i32 m0, s29, 0xe000
	s_nop 0
	global_load_lds_dwordx4 v[144:145], off
	s_waitcnt vmcnt(8)
	s_waitcnt lgkmcnt(0)
	s_barrier
; #define PG8_STAGE(bufoff, gbase, voff) do { _Pragma("unroll") for (int _i = 0; _i < 2; ++_i) \
;         __builtin_amdgcn_global_load_lds((const unsigned*)((const char*)(gbase) + (voff)[_i]), (PG8_LAS unsigned*)(lds + (bufoff) + ldsw + _i * 8192), 16, 0, 0); } while (0)
; #define PG8_LDA(dst, b, h) do { if constexpr (FP8) { _Pragma("unroll") for (int m = 0; m < 4; ++m) dst##8[m] = PG8_LD8(lds + PG8_SA(b, h) + aoff + m * 2048); } \
;         else { _Pragma("unroll") for (int m = 0; m < 4; ++m) _Pragma("unroll") for (int k = 0; k < 2; ++k) dst[m][k] = *(const PG8_LAS bf16x8*)(lds + PG8_SA(b, h) + aoff + m * 2048 + k * 1024); } } while (0)
; #define PG8_WAIT_V(n) asm volatile("s_waitcnt vmcnt(" #n ")" ::: "memory")
; #define PG8_WAIT_L(n) asm volatile("s_waitcnt lgkmcnt(" #n ")" ::: "memory")
; #define PG8_BAR __builtin_amdgcn_s_barrier()
; #define PG8_SCHED __builtin_amdgcn_sched_barrier(0)
; template <class Epi, class Sched, bool ALIGN_EPI = false, bool SP2 = false, bool FP8 = false, bool I8 = false>
; __device__ __forceinline__ void gemm_phase(PG8_LAS unsigned char* lds, const Gemm g, const Sched& S, const Epi& E, const SplitK sk) {
;     ...
;             PG8_WAIT_V(8); PG8_WAIT_L(0); PG8_BAR; PG8_MMA(0, 0, At, B0); PG8_MMA(0, 1, At, B1); PG8_BAR; PG8_SCHED;
;             PG8_LDA(At, 0, 1); PG8_STAGE(PG8_SB(0, 0), b2, voffB); PG8_STAGE(PG8_SB(0, 1), b2 + hstep, voffB); PG8_STAGE(PG8_SA(0, 0), a2, voffA);
;             PG8_WAIT_V(8); PG8_WAIT_L(0); PG8_BAR; PG8_MMA(1, 0, At, B0); PG8_MMA(1, 1, At, B1); PG8_BAR; PG8_SCHED;
	s_setprio 1
	s_waitcnt lgkmcnt(0)
	v_mfma_i32_16x16x64_i8 v[124:127], v[158:161], v[190:193], v[124:127]
	v_mfma_i32_16x16x64_i8 v[116:119], v[166:169], v[190:193], v[116:119]
	v_mfma_i32_16x16x64_i8 v[108:111], v[158:161], v[198:201], v[108:111]
	v_mfma_i32_16x16x64_i8 v[100:103], v[166:169], v[198:201], v[100:103]
	v_mfma_i32_16x16x64_i8 v[92:95], v[158:161], v[206:209], v[92:95]
	v_mfma_i32_16x16x64_i8 v[84:87], v[166:169], v[206:209], v[84:87]
	v_mfma_i32_16x16x64_i8 v[76:79], v[158:161], v[216:219], v[76:79]
	v_mfma_i32_16x16x64_i8 v[68:71], v[166:169], v[216:219], v[68:71]
	v_mfma_i32_16x16x64_i8 v[124:127], v[162:165], v[194:197], v[124:127]
	v_mfma_i32_16x16x64_i8 v[116:119], v[170:173], v[194:197], v[116:119]
	v_mfma_i32_16x16x64_i8 v[108:111], v[162:165], v[202:205], v[108:111]
	v_mfma_i32_16x16x64_i8 v[100:103], v[170:173], v[202:205], v[100:103]
	v_mfma_i32_16x16x64_i8 v[92:95], v[162:165], v[212:215], v[92:95]
	v_mfma_i32_16x16x64_i8 v[84:87], v[170:173], v[212:215], v[84:87]
	v_mfma_i32_16x16x64_i8 v[76:79], v[162:165], v[220:223], v[76:79]
	v_mfma_i32_16x16x64_i8 v[68:71], v[170:173], v[220:223], v[68:71]
	s_setprio 0
	s_setprio 1
	v_mfma_i32_16x16x64_i8 v[120:123], v[174:177], v[190:193], v[120:123]
	v_mfma_i32_16x16x64_i8 v[112:115], v[182:185], v[190:193], v[112:115]
	v_mfma_i32_16x16x64_i8 v[104:107], v[174:177], v[198:201], v[104:107]
	v_mfma_i32_16x16x64_i8 v[96:99], v[182:185], v[198:201], v[96:99]
	v_mfma_i32_16x16x64_i8 v[88:91], v[174:177], v[206:209], v[88:91]
	v_mfma_i32_16x16x64_i8 v[80:83], v[182:185], v[206:209], v[80:83]
	v_mfma_i32_16x16x64_i8 v[72:75], v[174:177], v[216:219], v[72:75]
	v_mfma_i32_16x16x64_i8 v[64:67], v[182:185], v[216:219], v[64:67]
	v_mfma_i32_16x16x64_i8 v[120:123], v[178:181], v[194:197], v[120:123]
	v_mfma_i32_16x16x64_i8 v[112:115], v[186:189], v[194:197], v[112:115]
	v_mfma_i32_16x16x64_i8 v[104:107], v[178:181], v[202:205], v[104:107]
	v_mfma_i32_16x16x64_i8 v[96:99], v[186:189], v[202:205], v[96:99]
	v_mfma_i32_16x16x64_i8 v[88:91], v[178:181], v[212:215], v[88:91]
	v_mfma_i32_16x16x64_i8 v[80:83], v[186:189], v[212:215], v[80:83]
	v_mfma_i32_16x16x64_i8 v[72:75], v[178:181], v[220:223], v[72:75]
	v_mfma_i32_16x16x64_i8 v[64:67], v[186:189], v[220:223], v[64:67]
	s_setprio 0
	s_barrier
	s_add_i32 s78, s63, s28
	v_lshl_add_u64 v[144:145], s[38:39], 0, v[130:131]
	s_mov_b32 m0, s78
	ds_read_b128 v[190:193], v149 offset:16384
	ds_read_b128 v[194:197], v149 offset:17408
	ds_read_b128 v[198:201], v149 offset:18432
	ds_read_b128 v[202:205], v149 offset:19456
	ds_read_b128 v[206:209], v149 offset:20480
	ds_read_b128 v[212:215], v149 offset:21504
	ds_read_b128 v[216:219], v149 offset:22528
	ds_read_b128 v[220:223], v149 offset:23552
	global_load_lds_dwordx4 v[144:145], off
	s_add_i32 m0, s78, 0x2000
	s_add_u32 s78, s38, 0x40000
	v_lshl_add_u64 v[224:225], s[38:39], 0, v[134:135]
	s_addc_u32 s79, s39, 0
	s_add_i32 s80, s64, s28
	global_load_lds_dwordx4 v[224:225], off
	v_lshl_add_u64 v[226:227], s[78:79], 0, v[130:131]
	s_mov_b32 m0, s80
	v_lshl_add_u64 v[228:229], s[40:41], 0, v[132:133]
	global_load_lds_dwordx4 v[226:227], off
	v_lshl_add_u64 v[226:227], s[78:79], 0, v[134:135]
	s_add_i32 m0, s80, 0x2000
	s_nop 0
	global_load_lds_dwordx4 v[226:227], off
	v_lshl_add_u64 v[226:227], s[40:41], 0, v[128:129]
	s_mov_b32 m0, s29
	s_nop 0
	global_load_lds_dwordx4 v[226:227], off
	s_mov_b32 m0, s30
	s_nop 0
	global_load_lds_dwordx4 v[228:229], off
	s_waitcnt vmcnt(8)
	s_waitcnt lgkmcnt(0)
	s_barrier
	s_setprio 1
	s_waitcnt lgkmcnt(0)
	v_mfma_i32_16x16x64_i8 v[60:63], v[158:161], v[190:193], v[60:63]
	v_mfma_i32_16x16x64_i8 v[52:55], v[166:169], v[190:193], v[52:55]
	v_mfma_i32_16x16x64_i8 v[44:47], v[158:161], v[198:201], v[44:47]
	v_mfma_i32_16x16x64_i8 v[36:39], v[166:169], v[198:201], v[36:39]
	v_mfma_i32_16x16x64_i8 v[28:31], v[158:161], v[206:209], v[28:31]
	v_mfma_i32_16x16x64_i8 v[20:23], v[166:169], v[206:209], v[20:23]
	v_mfma_i32_16x16x64_i8 v[12:15], v[158:161], v[216:219], v[12:15]
	v_mfma_i32_16x16x64_i8 v[4:7], v[166:169], v[216:219], v[4:7]
	v_mfma_i32_16x16x64_i8 v[60:63], v[162:165], v[194:197], v[60:63]
	v_mfma_i32_16x16x64_i8 v[52:55], v[170:173], v[194:197], v[52:55]
	v_mfma_i32_16x16x64_i8 v[44:47], v[162:165], v[202:205], v[44:47]
	v_mfma_i32_16x16x64_i8 v[36:39], v[170:173], v[202:205], v[36:39]
	v_mfma_i32_16x16x64_i8 v[28:31], v[162:165], v[212:215], v[28:31]
	v_mfma_i32_16x16x64_i8 v[20:23], v[170:173], v[212:215], v[20:23]
	v_mfma_i32_16x16x64_i8 v[12:15], v[162:165], v[220:223], v[12:15]
	v_mfma_i32_16x16x64_i8 v[4:7], v[170:173], v[220:223], v[4:7]
	s_setprio 0
	s_setprio 1
	v_mfma_i32_16x16x64_i8 v[56:59], v[174:177], v[190:193], v[56:59]
	v_mfma_i32_16x16x64_i8 v[48:51], v[182:185], v[190:193], v[48:51]
	v_mfma_i32_16x16x64_i8 v[40:43], v[174:177], v[198:201], v[40:43]
	v_mfma_i32_16x16x64_i8 v[32:35], v[182:185], v[198:201], v[32:35]
	v_mfma_i32_16x16x64_i8 v[24:27], v[174:177], v[206:209], v[24:27]
	v_mfma_i32_16x16x64_i8 v[16:19], v[182:185], v[206:209], v[16:19]
	v_mfma_i32_16x16x64_i8 v[8:11], v[174:177], v[216:219], v[8:11]
	v_mfma_i32_16x16x64_i8 v[0:3], v[182:185], v[216:219], v[0:3]
	v_mfma_i32_16x16x64_i8 v[56:59], v[178:181], v[194:197], v[56:59]
	v_mfma_i32_16x16x64_i8 v[48:51], v[186:189], v[194:197], v[48:51]
	v_mfma_i32_16x16x64_i8 v[40:43], v[178:181], v[202:205], v[40:43]
	v_mfma_i32_16x16x64_i8 v[32:35], v[186:189], v[202:205], v[32:35]
	v_mfma_i32_16x16x64_i8 v[24:27], v[178:181], v[212:215], v[24:27]
	v_mfma_i32_16x16x64_i8 v[16:19], v[186:189], v[212:215], v[16:19]
	v_mfma_i32_16x16x64_i8 v[8:11], v[178:181], v[220:223], v[8:11]
	v_mfma_i32_16x16x64_i8 v[0:3], v[186:189], v[220:223], v[0:3]
	s_setprio 0
	s_barrier
; #define PG8_STAGE(bufoff, gbase, voff) do { _Pragma("unroll") for (int _i = 0; _i < 2; ++_i) \
;         __builtin_amdgcn_global_load_lds((const unsigned*)((const char*)(gbase) + (voff)[_i]), (PG8_LAS unsigned*)(lds + (bufoff) + ldsw + _i * 8192), 16, 0, 0); } while (0)
; #define PG8_LDA(dst, b, h) do { if constexpr (FP8) { _Pragma("unroll") for (int m = 0; m < 4; ++m) dst##8[m] = PG8_LD8(lds + PG8_SA(b, h) + aoff + m * 2048); } \
;         else { _Pragma("unroll") for (int m = 0; m < 4; ++m) _Pragma("unroll") for (int k = 0; k < 2; ++k) dst[m][k] = *(const PG8_LAS bf16x8*)(lds + PG8_SA(b, h) + aoff + m * 2048 + k * 1024); } } while (0)
; #define PG8_LDB(dst, b, h) do { if constexpr (FP8) { _Pragma("unroll") for (int n = 0; n < 2; ++n) dst##8[n] = PG8_LD8(lds + PG8_SB(b, h) + boff + n * 2048); } \
;         else { _Pragma("unroll") for (int n = 0; n < 2; ++n) _Pragma("unroll") for (int k = 0; k < 2; ++k) dst[n][k] = *(const PG8_LAS bf16x8*)(lds + PG8_SB(b, h) + boff + n * 2048 + k * 1024); } } while (0)
; #define PG8_WAIT_V(n) asm volatile("s_waitcnt vmcnt(" #n ")" ::: "memory")
; #define PG8_WAIT_L(n) asm volatile("s_waitcnt lgkmcnt(" #n ")" ::: "memory")
; #define PG8_BAR __builtin_amdgcn_s_barrier()
; #define PG8_SCHED __builtin_amdgcn_sched_barrier(0)
; template <class Epi, class Sched, bool ALIGN_EPI = false, bool SP2 = false, bool FP8 = false, bool I8 = false>
; __device__ __forceinline__ void gemm_phase(PG8_LAS unsigned char* lds, const Gemm g, const Sched& S, const Epi& E, const SplitK sk) {
;     ...
;             PG8_LDB(B0, 1, 0); PG8_LDB(B1, 1, 1); PG8_SCHED; PG8_LDA(At, 1, 0); PG8_STAGE(PG8_SA(0, 1), a2 + hstep, voffA);
;             PG8_WAIT_V(8); PG8_WAIT_L(0); PG8_BAR; PG8_MMA(0, 0, At, B0); PG8_MMA(0, 1, At, B1); PG8_BAR; PG8_SCHED;
	s_add_i32 s78, 0, 0x18000
	v_add_u32_e32 v136, s78, v148
	s_add_i32 s79, 0, 0x1c000
	ds_read_b128 v[158:161], v136
	ds_read_b128 v[162:165], v136 offset:1024
	ds_read_b128 v[166:169], v136 offset:2048
	ds_read_b128 v[170:173], v136 offset:3072
	v_add_u32_e32 v136, s79, v148
	ds_read_b128 v[174:177], v136
	ds_read_b128 v[178:181], v136 offset:1024
	ds_read_b128 v[182:185], v136 offset:2048
	ds_read_b128 v[186:189], v136 offset:3072
	s_add_u32 s40, s40, 0x40000
	s_addc_u32 s41, s41, 0
	s_mov_b32 m0, s31
	v_lshl_add_u64 v[230:231], s[40:41], 0, v[128:129]
	ds_read_b128 v[190:193], v149 offset:32768
	ds_read_b128 v[194:197], v149 offset:33792
	ds_read_b128 v[198:201], v149 offset:34816
	ds_read_b128 v[202:205], v149 offset:35840
	ds_read_b128 v[206:209], v149 offset:36864
	ds_read_b128 v[212:215], v149 offset:37888
	ds_read_b128 v[216:219], v149 offset:38912
	ds_read_b128 v[220:223], v149 offset:39936
	global_load_lds_dwordx4 v[230:231], off
	v_lshl_add_u64 v[230:231], s[40:41], 0, v[132:133]
	s_mov_b32 m0, s33
	s_nop 0
	global_load_lds_dwordx4 v[230:231], off
	s_waitcnt vmcnt(8)
	s_waitcnt lgkmcnt(0)
	s_barrier
	s_setprio 1
	s_waitcnt lgkmcnt(0)
	v_mfma_i32_16x16x64_i8 v[124:127], v[158:161], v[190:193], v[124:127]
	v_mfma_i32_16x16x64_i8 v[116:119], v[166:169], v[190:193], v[116:119]
	v_mfma_i32_16x16x64_i8 v[108:111], v[158:161], v[198:201], v[108:111]
	v_mfma_i32_16x16x64_i8 v[100:103], v[166:169], v[198:201], v[100:103]
	v_mfma_i32_16x16x64_i8 v[92:95], v[158:161], v[206:209], v[92:95]
	v_mfma_i32_16x16x64_i8 v[84:87], v[166:169], v[206:209], v[84:87]
	v_mfma_i32_16x16x64_i8 v[76:79], v[158:161], v[216:219], v[76:79]
	v_mfma_i32_16x16x64_i8 v[68:71], v[166:169], v[216:219], v[68:71]
	v_mfma_i32_16x16x64_i8 v[124:127], v[162:165], v[194:197], v[124:127]
	v_mfma_i32_16x16x64_i8 v[116:119], v[170:173], v[194:197], v[116:119]
	v_mfma_i32_16x16x64_i8 v[108:111], v[162:165], v[202:205], v[108:111]
	v_mfma_i32_16x16x64_i8 v[100:103], v[170:173], v[202:205], v[100:103]
	v_mfma_i32_16x16x64_i8 v[92:95], v[162:165], v[212:215], v[92:95]
	v_mfma_i32_16x16x64_i8 v[84:87], v[170:173], v[212:215], v[84:87]
	v_mfma_i32_16x16x64_i8 v[76:79], v[162:165], v[220:223], v[76:79]
	v_mfma_i32_16x16x64_i8 v[68:71], v[170:173], v[220:223], v[68:71]
	s_setprio 0
	s_setprio 1
	v_mfma_i32_16x16x64_i8 v[120:123], v[174:177], v[190:193], v[120:123]
	v_mfma_i32_16x16x64_i8 v[112:115], v[182:185], v[190:193], v[112:115]
	v_mfma_i32_16x16x64_i8 v[104:107], v[174:177], v[198:201], v[104:107]
	v_mfma_i32_16x16x64_i8 v[96:99], v[182:185], v[198:201], v[96:99]
	v_mfma_i32_16x16x64_i8 v[88:91], v[174:177], v[206:209], v[88:91]
	v_mfma_i32_16x16x64_i8 v[80:83], v[182:185], v[206:209], v[80:83]
	v_mfma_i32_16x16x64_i8 v[72:75], v[174:177], v[216:219], v[72:75]
	v_mfma_i32_16x16x64_i8 v[64:67], v[182:185], v[216:219], v[64:67]
	v_mfma_i32_16x16x64_i8 v[120:123], v[178:181], v[194:197], v[120:123]
	v_mfma_i32_16x16x64_i8 v[112:115], v[186:189], v[194:197], v[112:115]
	v_mfma_i32_16x16x64_i8 v[104:107], v[178:181], v[202:205], v[104:107]
	v_mfma_i32_16x16x64_i8 v[96:99], v[186:189], v[202:205], v[96:99]
	v_mfma_i32_16x16x64_i8 v[88:91], v[178:181], v[212:215], v[88:91]
	v_mfma_i32_16x16x64_i8 v[80:83], v[186:189], v[212:215], v[80:83]
	v_mfma_i32_16x16x64_i8 v[72:75], v[178:181], v[220:223], v[72:75]
	v_mfma_i32_16x16x64_i8 v[64:67], v[186:189], v[220:223], v[64:67]
	s_setprio 0
	s_barrier
; #define PG8_STAGE(bufoff, gbase, voff) do { _Pragma("unroll") for (int _i = 0; _i < 2; ++_i) \
;         __builtin_amdgcn_global_load_lds((const unsigned*)((const char*)(gbase) + (voff)[_i]), (PG8_LAS unsigned*)(lds + (bufoff) + ldsw + _i * 8192), 16, 0, 0); } while (0)
; #define PG8_LDA(dst, b, h) do { if constexpr (FP8) { _Pragma("unroll") for (int m = 0; m < 4; ++m) dst##8[m] = PG8_LD8(lds + PG8_SA(b, h) + aoff + m * 2048); } \
;         else { _Pragma("unroll") for (int m = 0; m < 4; ++m) _Pragma("unroll") for (int k = 0; k < 2; ++k) dst[m][k] = *(const PG8_LAS bf16x8*)(lds + PG8_SA(b, h) + aoff + m * 2048 + k * 1024); } } while (0)
; #define PG8_WAIT_V(n) asm volatile("s_waitcnt vmcnt(" #n ")" ::: "memory")
; #define PG8_WAIT_L(n) asm volatile("s_waitcnt lgkmcnt(" #n ")" ::: "memory")
; #define PG8_BAR __builtin_amdgcn_s_barrier()
; #define PG8_SCHED __builtin_amdgcn_sched_barrier(0)
; template <class Epi, class Sched, bool ALIGN_EPI = false, bool SP2 = false, bool FP8 = false, bool I8 = false>
; __device__ __forceinline__ void gemm_phase(PG8_LAS unsigned char* lds, const Gemm g, const Sched& S, const Epi& E, const SplitK sk) {
;     ...
;             PG8_LDA(At, 1, 1); PG8_STAGE(PG8_SB(1, 0), b3, voffB); PG8_STAGE(PG8_SB(1, 1), b3 + hstep, voffB); PG8_STAGE(PG8_SA(1, 0), a3, voffA);
;             PG8_WAIT_V(8); PG8_WAIT_L(0); PG8_BAR; PG8_MMA(1, 0, At, B0); PG8_MMA(1, 1, At, B1); PG8_BAR; PG8_SCHED;
;     ...
;         if constexpr (ALIGN_EPI) { if (wr == 0) PG8_BAR; }
	s_add_i32 s40, s78, s28
	v_lshl_add_u64 v[144:145], v[144:145], 0, s[8:9]
	s_mov_b32 m0, s40
	ds_read_b128 v[190:193], v149 offset:49152
	ds_read_b128 v[194:197], v149 offset:50176
	ds_read_b128 v[198:201], v149 offset:51200
	ds_read_b128 v[202:205], v149 offset:52224
	ds_read_b128 v[206:209], v149 offset:53248
	ds_read_b128 v[212:215], v149 offset:54272
	ds_read_b128 v[216:219], v149 offset:55296
	ds_read_b128 v[220:223], v149 offset:56320
	global_load_lds_dwordx4 v[144:145], off
	s_add_i32 m0, s40, 0x2000
	s_add_u32 s38, s38, 0x40080
	v_lshl_add_u64 v[144:145], v[224:225], 0, s[8:9]
	s_addc_u32 s39, s39, 0
	s_add_i32 s40, s79, s28
	global_load_lds_dwordx4 v[144:145], off
	v_lshl_add_u64 v[144:145], s[38:39], 0, v[130:131]
	s_mov_b32 m0, s40
	s_nop 0
	global_load_lds_dwordx4 v[144:145], off
	v_lshl_add_u64 v[144:145], s[38:39], 0, v[134:135]
	s_add_i32 m0, s40, 0x2000
	s_nop 0
	global_load_lds_dwordx4 v[144:145], off
	v_lshl_add_u64 v[144:145], v[226:227], 0, s[8:9]
	s_mov_b32 m0, s58
	s_nop 0
	global_load_lds_dwordx4 v[144:145], off
	v_lshl_add_u64 v[144:145], v[228:229], 0, s[8:9]
	s_mov_b32 m0, s59
	s_nop 0
	global_load_lds_dwordx4 v[144:145], off
	s_waitcnt vmcnt(8)
	s_waitcnt lgkmcnt(0)
	s_barrier
	s_setprio 1
	s_waitcnt lgkmcnt(0)
	v_mfma_i32_16x16x64_i8 v[60:63], v[158:161], v[190:193], v[60:63]
	v_mfma_i32_16x16x64_i8 v[52:55], v[166:169], v[190:193], v[52:55]
	v_mfma_i32_16x16x64_i8 v[44:47], v[158:161], v[198:201], v[44:47]
	v_mfma_i32_16x16x64_i8 v[36:39], v[166:169], v[198:201], v[36:39]
	v_mfma_i32_16x16x64_i8 v[28:31], v[158:161], v[206:209], v[28:31]
	v_mfma_i32_16x16x64_i8 v[20:23], v[166:169], v[206:209], v[20:23]
	v_mfma_i32_16x16x64_i8 v[12:15], v[158:161], v[216:219], v[12:15]
	v_mfma_i32_16x16x64_i8 v[4:7], v[166:169], v[216:219], v[4:7]
	v_mfma_i32_16x16x64_i8 v[60:63], v[162:165], v[194:197], v[60:63]
	v_mfma_i32_16x16x64_i8 v[52:55], v[170:173], v[194:197], v[52:55]
	v_mfma_i32_16x16x64_i8 v[44:47], v[162:165], v[202:205], v[44:47]
	v_mfma_i32_16x16x64_i8 v[36:39], v[170:173], v[202:205], v[36:39]
	v_mfma_i32_16x16x64_i8 v[28:31], v[162:165], v[212:215], v[28:31]
	v_mfma_i32_16x16x64_i8 v[20:23], v[170:173], v[212:215], v[20:23]
	v_mfma_i32_16x16x64_i8 v[12:15], v[162:165], v[220:223], v[12:15]
	v_mfma_i32_16x16x64_i8 v[4:7], v[170:173], v[220:223], v[4:7]
	s_setprio 0
	s_setprio 1
	v_mfma_i32_16x16x64_i8 v[56:59], v[174:177], v[190:193], v[56:59]
	v_mfma_i32_16x16x64_i8 v[48:51], v[182:185], v[190:193], v[48:51]
	v_mfma_i32_16x16x64_i8 v[40:43], v[174:177], v[198:201], v[40:43]
	v_mfma_i32_16x16x64_i8 v[32:35], v[182:185], v[198:201], v[32:35]
	v_mfma_i32_16x16x64_i8 v[24:27], v[174:177], v[206:209], v[24:27]
	v_mfma_i32_16x16x64_i8 v[16:19], v[182:185], v[206:209], v[16:19]
	v_mfma_i32_16x16x64_i8 v[8:11], v[174:177], v[216:219], v[8:11]
	v_mfma_i32_16x16x64_i8 v[0:3], v[182:185], v[216:219], v[0:3]
	v_mfma_i32_16x16x64_i8 v[56:59], v[178:181], v[194:197], v[56:59]
	v_mfma_i32_16x16x64_i8 v[48:51], v[186:189], v[194:197], v[48:51]
	v_mfma_i32_16x16x64_i8 v[40:43], v[178:181], v[202:205], v[40:43]
	v_mfma_i32_16x16x64_i8 v[32:35], v[186:189], v[202:205], v[32:35]
	v_mfma_i32_16x16x64_i8 v[24:27], v[178:181], v[212:215], v[24:27]
	v_mfma_i32_16x16x64_i8 v[16:19], v[186:189], v[212:215], v[16:19]
	v_mfma_i32_16x16x64_i8 v[8:11], v[178:181], v[220:223], v[8:11]
	v_mfma_i32_16x16x64_i8 v[0:3], v[186:189], v[220:223], v[0:3]
	s_setprio 0
	s_barrier
	s_add_u32 s20, s20, 0x100
	s_addc_u32 s21, s21, 0
	s_add_u32 s75, s75, 0x100
	s_addc_u32 s76, s76, 0
	s_cmp_ge_i32 s77, s43
	s_mov_b32 s38, s77
	s_cbranch_scc0 .LBB0_1223
	s_and_b64 vcc, exec, s[10:11]
	s_cbranch_vccz .LBB0_1226
	s_barrier
